# PL1: code placement: the 10 GEMM K-loop heads aligned to 64 bytes (.p2align 6); on top of BE1
# baseline (speedup 1.0000x reference)
.LBB0_285:
	s_add_u32 s8, s26, 0x100
	s_addc_u32 s9, s27, 0
	s_add_u32 s18, s20, 0x100
	s_addc_u32 s19, s21, 0
	s_and_b64 s[16:17], s[64:65], exec
	s_cselect_b32 s31, s51, s19
	s_cselect_b32 s30, s50, s18
	s_add_i32 s46, 0, 0x10000
	s_and_b64 s[16:17], s[64:65], exec
	s_cselect_b32 s19, s15, s9
	s_cselect_b32 s18, s14, s8
	s_add_i32 s8, 0, 0x14000
	v_add_u32_e32 v2, s46, v198
	v_add_u32_e32 v132, s8, v198
	ds_read_b128 v[4:7], v2
	ds_read_b128 v[8:11], v2 offset:1024
	ds_read_b128 v[12:15], v2 offset:2048
	ds_read_b128 v[16:19], v2 offset:3072
	ds_read_b128 v[20:23], v132
	ds_read_b128 v[24:27], v132 offset:1024
	ds_read_b128 v[28:31], v132 offset:2048
	ds_read_b128 v[32:35], v132 offset:3072
	s_add_u32 s16, s26, 0x80
	s_addc_u32 s17, s27, 0
	s_add_i32 s42, s85, 0x8000
	s_add_i32 s43, s85, 0xa000
	s_mov_b64 s[28:29], s[16:17]
	s_mov_b32 m0, s42
	s_add_u32 s16, s16, s54
	ds_read_b128 v[36:39], v199 offset:8192
	ds_read_b128 v[40:43], v199 offset:9216
	ds_read_b128 v[44:47], v199 offset:10240
	ds_read_b128 v[48:51], v199 offset:11264
	ds_read_b128 v[52:55], v199 offset:12288
	ds_read_b128 v[56:59], v199 offset:13312
	ds_read_b128 v[60:63], v199 offset:14336
	ds_read_b128 v[64:67], v199 offset:15360
	s_addc_u32 s17, s17, s55
	global_load_lds_dwordx4 v194, s[28:29]
	s_mov_b32 m0, s43
	s_add_i32 s44, s85, 0xc000
	global_load_lds_dwordx4 v195, s[28:29]
	s_mov_b32 m0, s44
	s_add_i32 s45, s85, 0xe000
	s_add_u32 s28, s30, 0x80
	global_load_lds_dwordx4 v194, s[16:17]
	s_mov_b32 m0, s45
	s_addc_u32 s29, s31, 0
	global_load_lds_dwordx4 v195, s[16:17]
	s_waitcnt vmcnt(8)
	s_waitcnt lgkmcnt(0)
	s_barrier
	s_setprio 1
	s_waitcnt lgkmcnt(0)
	v_mfma_f32_16x16x32_bf16 v[68:71], v[4:7], v[36:39], 0
	v_mfma_f32_16x16x32_bf16 v[72:75], v[12:15], v[36:39], 0
	v_mfma_f32_16x16x32_bf16 v[76:79], v[4:7], v[44:47], 0
	v_mfma_f32_16x16x32_bf16 v[80:83], v[12:15], v[44:47], 0
	v_mfma_f32_16x16x32_bf16 v[84:87], v[4:7], v[52:55], 0
	v_mfma_f32_16x16x32_bf16 v[88:91], v[12:15], v[52:55], 0
	v_mfma_f32_16x16x32_bf16 v[92:95], v[4:7], v[60:63], 0
	v_mfma_f32_16x16x32_bf16 v[96:99], v[12:15], v[60:63], 0
	v_mfma_f32_16x16x32_bf16 v[68:71], v[8:11], v[40:43], v[68:71]
	v_mfma_f32_16x16x32_bf16 v[72:75], v[16:19], v[40:43], v[72:75]
	v_mfma_f32_16x16x32_bf16 v[76:79], v[8:11], v[48:51], v[76:79]
	v_mfma_f32_16x16x32_bf16 v[80:83], v[16:19], v[48:51], v[80:83]
	v_mfma_f32_16x16x32_bf16 v[84:87], v[8:11], v[56:59], v[84:87]
	v_mfma_f32_16x16x32_bf16 v[88:91], v[16:19], v[56:59], v[88:91]
	v_mfma_f32_16x16x32_bf16 v[92:95], v[8:11], v[64:67], v[92:95]
	v_mfma_f32_16x16x32_bf16 v[96:99], v[16:19], v[64:67], v[96:99]
	s_setprio 0
	s_setprio 1
	v_mfma_f32_16x16x32_bf16 v[100:103], v[20:23], v[36:39], 0
	v_mfma_f32_16x16x32_bf16 v[36:39], v[28:31], v[36:39], 0
	v_mfma_f32_16x16x32_bf16 v[100:103], v[24:27], v[40:43], v[100:103]
	v_mfma_f32_16x16x32_bf16 v[40:43], v[32:35], v[40:43], v[36:39]
	v_mfma_f32_16x16x32_bf16 v[36:39], v[20:23], v[44:47], 0
	v_mfma_f32_16x16x32_bf16 v[104:107], v[24:27], v[48:51], v[36:39]
	v_mfma_f32_16x16x32_bf16 v[36:39], v[28:31], v[44:47], 0
	v_mfma_f32_16x16x32_bf16 v[48:51], v[32:35], v[48:51], v[36:39]
	v_mfma_f32_16x16x32_bf16 v[36:39], v[20:23], v[52:55], 0
	v_mfma_f32_16x16x32_bf16 v[108:111], v[24:27], v[56:59], v[36:39]
	v_mfma_f32_16x16x32_bf16 v[36:39], v[28:31], v[52:55], 0
	v_mfma_f32_16x16x32_bf16 v[56:59], v[32:35], v[56:59], v[36:39]
	v_mfma_f32_16x16x32_bf16 v[36:39], v[20:23], v[60:63], 0
	v_mfma_f32_16x16x32_bf16 v[112:115], v[24:27], v[64:67], v[36:39]
	v_mfma_f32_16x16x32_bf16 v[36:39], v[28:31], v[60:63], 0
	v_mfma_f32_16x16x32_bf16 v[64:67], v[32:35], v[64:67], v[36:39]
	s_setprio 0
	s_barrier
	s_add_i32 s46, s46, s83
	s_mov_b64 s[16:17], s[30:31]
	s_mov_b32 m0, s46
	s_add_i32 s47, s46, 0x2000
	s_nop 0
	ds_read_b128 v[36:39], v199 offset:24576
	ds_read_b128 v[44:47], v199 offset:25600
	ds_read_b128 v[52:55], v199 offset:26624
	ds_read_b128 v[60:63], v199 offset:27648
	ds_read_b128 v[116:119], v199 offset:28672
	ds_read_b128 v[120:123], v199 offset:29696
	ds_read_b128 v[124:127], v199 offset:30720
	ds_read_b128 v[128:131], v199 offset:31744
	s_nop 0
	global_load_lds_dwordx4 v201, s[16:17]
	s_mov_b32 m0, s47
	s_nop 0
	global_load_lds_dwordx4 v200, s[16:17]
	s_add_u32 s16, s30, s54
	s_addc_u32 s17, s31, s55
	s_add_i32 s30, s8, s83
	s_mov_b32 m0, s30
	s_add_i32 s31, s30, 0x2000
	s_nop 0
	global_load_lds_dwordx4 v201, s[16:17]
	s_mov_b32 m0, s31
	s_nop 0
	global_load_lds_dwordx4 v200, s[16:17]
	s_waitcnt vmcnt(6)
	s_waitcnt lgkmcnt(0)
	s_barrier
	s_setprio 1
	s_waitcnt lgkmcnt(0)
	v_mfma_f32_16x16x32_bf16 v[134:137], v[4:7], v[36:39], 0
	v_mfma_f32_16x16x32_bf16 v[144:147], v[4:7], v[52:55], 0
	v_mfma_f32_16x16x32_bf16 v[152:155], v[4:7], v[116:119], 0
	v_mfma_f32_16x16x32_bf16 v[4:7], v[4:7], v[124:127], 0
	v_mfma_f32_16x16x32_bf16 v[140:143], v[12:15], v[36:39], 0
	v_mfma_f32_16x16x32_bf16 v[148:151], v[12:15], v[52:55], 0
	v_mfma_f32_16x16x32_bf16 v[156:159], v[12:15], v[116:119], 0
	v_mfma_f32_16x16x32_bf16 v[160:163], v[8:11], v[128:131], v[4:7]
	v_mfma_f32_16x16x32_bf16 v[4:7], v[12:15], v[124:127], 0
	v_mfma_f32_16x16x32_bf16 v[136:139], v[8:11], v[44:47], v[134:137]
	v_mfma_f32_16x16x32_bf16 v[140:143], v[16:19], v[44:47], v[140:143]
	v_mfma_f32_16x16x32_bf16 v[144:147], v[8:11], v[60:63], v[144:147]
	v_mfma_f32_16x16x32_bf16 v[148:151], v[16:19], v[60:63], v[148:151]
	v_mfma_f32_16x16x32_bf16 v[152:155], v[8:11], v[120:123], v[152:155]
	v_mfma_f32_16x16x32_bf16 v[156:159], v[16:19], v[120:123], v[156:159]
	v_mfma_f32_16x16x32_bf16 v[164:167], v[16:19], v[128:131], v[4:7]
	s_setprio 0
	s_setprio 1
	v_mfma_f32_16x16x32_bf16 v[4:7], v[20:23], v[36:39], 0
	v_mfma_f32_16x16x32_bf16 v[168:171], v[24:27], v[44:47], v[4:7]
	v_mfma_f32_16x16x32_bf16 v[4:7], v[28:31], v[36:39], 0
	v_mfma_f32_16x16x32_bf16 v[172:175], v[32:35], v[44:47], v[4:7]
	v_mfma_f32_16x16x32_bf16 v[4:7], v[20:23], v[52:55], 0
	v_mfma_f32_16x16x32_bf16 v[176:179], v[24:27], v[60:63], v[4:7]
	v_mfma_f32_16x16x32_bf16 v[4:7], v[28:31], v[52:55], 0
	v_mfma_f32_16x16x32_bf16 v[180:183], v[32:35], v[60:63], v[4:7]
	v_mfma_f32_16x16x32_bf16 v[4:7], v[20:23], v[116:119], 0
	v_mfma_f32_16x16x32_bf16 v[184:187], v[24:27], v[120:123], v[4:7]
	v_mfma_f32_16x16x32_bf16 v[4:7], v[28:31], v[116:119], 0
	v_mfma_f32_16x16x32_bf16 v[120:123], v[32:35], v[120:123], v[4:7]
	v_mfma_f32_16x16x32_bf16 v[4:7], v[20:23], v[124:127], 0
	v_mfma_f32_16x16x32_bf16 v[188:191], v[24:27], v[128:131], v[4:7]
	v_mfma_f32_16x16x32_bf16 v[4:7], v[28:31], v[124:127], 0
	v_mfma_f32_16x16x32_bf16 v[128:131], v[32:35], v[128:131], v[4:7]
	s_setprio 0
	s_barrier
	s_add_i32 s48, 0, 0x18000
	s_add_i32 s8, 0, 0x1c000
	v_add_u32_e32 v133, s48, v198
	v_add_u32_e32 v134, s8, v198
	ds_read_b128 v[116:119], v133
	ds_read_b128 v[124:127], v133 offset:1024
	ds_read_b128 v[202:205], v133 offset:2048
	ds_read_b128 v[206:209], v133 offset:3072
	ds_read_b128 v[216:219], v134
	ds_read_b128 v[220:223], v134 offset:1024
	ds_read_b128 v[224:227], v134 offset:2048
	ds_read_b128 v[228:231], v134 offset:3072
	s_mov_b32 m0, s85
	s_mov_b64 s[16:17], s[18:19]
	ds_read_b128 v[44:47], v199 offset:40960
	ds_read_b128 v[52:55], v199 offset:41984
	ds_read_b128 v[60:63], v199 offset:43008
	ds_read_b128 v[232:235], v199 offset:44032
	ds_read_b128 v[236:239], v199 offset:45056
	ds_read_b128 v[242:245], v199 offset:46080
	ds_read_b128 v[246:249], v199 offset:47104
	ds_read_b128 v[250:253], v199 offset:48128
	s_nop 0
	global_load_lds_dwordx4 v194, s[16:17]
	s_mov_b32 m0, s86
	s_nop 0
	global_load_lds_dwordx4 v195, s[16:17]
	s_add_u32 s16, s18, s54
	s_addc_u32 s17, s19, s55
	s_mov_b32 m0, s87
	s_nop 0
	global_load_lds_dwordx4 v194, s[16:17]
	s_mov_b32 m0, s88
	s_nop 0
	global_load_lds_dwordx4 v195, s[16:17]
	s_waitcnt vmcnt(8)
	s_waitcnt lgkmcnt(0)
	s_barrier
	s_setprio 1
	s_waitcnt lgkmcnt(0)
	v_mfma_f32_16x16x32_bf16 v[4:7], v[116:119], v[44:47], v[68:71]
	v_mfma_f32_16x16x32_bf16 v[4:7], v[124:127], v[52:55], v[4:7]
	v_mfma_f32_16x16x32_bf16 v[8:11], v[202:205], v[44:47], v[72:75]
	v_mfma_f32_16x16x32_bf16 v[8:11], v[206:209], v[52:55], v[8:11]
	v_mfma_f32_16x16x32_bf16 v[12:15], v[116:119], v[60:63], v[76:79]
	v_mfma_f32_16x16x32_bf16 v[12:15], v[124:127], v[232:235], v[12:15]
	v_mfma_f32_16x16x32_bf16 v[16:19], v[202:205], v[60:63], v[80:83]
	v_mfma_f32_16x16x32_bf16 v[16:19], v[206:209], v[232:235], v[16:19]
	v_mfma_f32_16x16x32_bf16 v[20:23], v[116:119], v[236:239], v[84:87]
	v_mfma_f32_16x16x32_bf16 v[20:23], v[124:127], v[242:245], v[20:23]
	v_mfma_f32_16x16x32_bf16 v[24:27], v[202:205], v[236:239], v[88:91]
	v_mfma_f32_16x16x32_bf16 v[24:27], v[206:209], v[242:245], v[24:27]
	v_mfma_f32_16x16x32_bf16 v[28:31], v[116:119], v[246:249], v[92:95]
	v_mfma_f32_16x16x32_bf16 v[28:31], v[124:127], v[250:253], v[28:31]
	v_mfma_f32_16x16x32_bf16 v[32:35], v[202:205], v[246:249], v[96:99]
	v_mfma_f32_16x16x32_bf16 v[32:35], v[206:209], v[250:253], v[32:35]
	s_setprio 0
	s_setprio 1
	v_mfma_f32_16x16x32_bf16 v[36:39], v[216:219], v[44:47], v[100:103]
	v_mfma_f32_16x16x32_bf16 v[40:43], v[224:227], v[44:47], v[40:43]
	v_mfma_f32_16x16x32_bf16 v[36:39], v[220:223], v[52:55], v[36:39]
	v_mfma_f32_16x16x32_bf16 v[40:43], v[228:231], v[52:55], v[40:43]
	v_mfma_f32_16x16x32_bf16 v[44:47], v[216:219], v[60:63], v[104:107]
	v_mfma_f32_16x16x32_bf16 v[48:51], v[224:227], v[60:63], v[48:51]
	v_mfma_f32_16x16x32_bf16 v[52:55], v[216:219], v[236:239], v[108:111]
	v_mfma_f32_16x16x32_bf16 v[56:59], v[224:227], v[236:239], v[56:59]
	v_mfma_f32_16x16x32_bf16 v[60:63], v[216:219], v[246:249], v[112:115]
	v_mfma_f32_16x16x32_bf16 v[64:67], v[224:227], v[246:249], v[64:67]
	v_mfma_f32_16x16x32_bf16 v[44:47], v[220:223], v[232:235], v[44:47]
	v_mfma_f32_16x16x32_bf16 v[48:51], v[228:231], v[232:235], v[48:51]
	v_mfma_f32_16x16x32_bf16 v[52:55], v[220:223], v[242:245], v[52:55]
	v_mfma_f32_16x16x32_bf16 v[56:59], v[228:231], v[242:245], v[56:59]
	v_mfma_f32_16x16x32_bf16 v[60:63], v[220:223], v[250:253], v[60:63]
	v_mfma_f32_16x16x32_bf16 v[64:67], v[228:231], v[250:253], v[64:67]
	s_setprio 0
	s_barrier
	s_add_i32 s48, s48, s83
	s_mov_b64 s[16:17], s[28:29]
	s_mov_b32 m0, s48
	s_add_i32 s49, s48, 0x2000
	ds_read_b128 v[104:107], v199 offset:57344
	ds_read_b128 v[108:111], v199 offset:58368
	ds_read_b128 v[112:115], v199 offset:59392
	ds_read_b128 v[232:235], v199 offset:60416
	ds_read_b128 v[236:239], v199 offset:61440
	ds_read_b128 v[242:245], v199 offset:62464
	ds_read_b128 v[246:249], v199 offset:63488
	ds_read_b128 v[250:253], v199 offset:64512
	s_nop 0
	global_load_lds_dwordx4 v201, s[16:17]
	s_mov_b32 m0, s49
	s_nop 0
	global_load_lds_dwordx4 v200, s[16:17]
	s_add_u32 s16, s28, s54
	s_addc_u32 s17, s29, s55
	s_add_i32 s28, s8, s83
	s_mov_b32 m0, s28
	s_add_i32 s29, s28, 0x2000
	s_nop 0
	global_load_lds_dwordx4 v201, s[16:17]
	s_mov_b32 m0, s29
	s_nop 0
	global_load_lds_dwordx4 v200, s[16:17]
	s_waitcnt vmcnt(6)
	s_waitcnt lgkmcnt(0)
	s_barrier
	s_setprio 1
	s_waitcnt lgkmcnt(0)
	v_mfma_f32_16x16x32_bf16 v[68:71], v[116:119], v[104:107], v[136:139]
	v_mfma_f32_16x16x32_bf16 v[68:71], v[124:127], v[108:111], v[68:71]
	v_mfma_f32_16x16x32_bf16 v[72:75], v[202:205], v[104:107], v[140:143]
	v_mfma_f32_16x16x32_bf16 v[72:75], v[206:209], v[108:111], v[72:75]
	v_mfma_f32_16x16x32_bf16 v[76:79], v[116:119], v[112:115], v[144:147]
	v_mfma_f32_16x16x32_bf16 v[76:79], v[124:127], v[232:235], v[76:79]
	v_mfma_f32_16x16x32_bf16 v[80:83], v[202:205], v[112:115], v[148:151]
	v_mfma_f32_16x16x32_bf16 v[80:83], v[206:209], v[232:235], v[80:83]
	v_mfma_f32_16x16x32_bf16 v[84:87], v[116:119], v[236:239], v[152:155]
	v_mfma_f32_16x16x32_bf16 v[84:87], v[124:127], v[242:245], v[84:87]
	v_mfma_f32_16x16x32_bf16 v[88:91], v[202:205], v[236:239], v[156:159]
	v_mfma_f32_16x16x32_bf16 v[88:91], v[206:209], v[242:245], v[88:91]
	v_mfma_f32_16x16x32_bf16 v[92:95], v[116:119], v[246:249], v[160:163]
	v_mfma_f32_16x16x32_bf16 v[92:95], v[124:127], v[250:253], v[92:95]
	v_mfma_f32_16x16x32_bf16 v[96:99], v[202:205], v[246:249], v[164:167]
	v_mfma_f32_16x16x32_bf16 v[96:99], v[206:209], v[250:253], v[96:99]
	s_setprio 0
	s_setprio 1
	v_mfma_f32_16x16x32_bf16 v[100:103], v[216:219], v[104:107], v[168:171]
	v_mfma_f32_16x16x32_bf16 v[104:107], v[224:227], v[104:107], v[172:175]
	v_mfma_f32_16x16x32_bf16 v[100:103], v[220:223], v[108:111], v[100:103]
	v_mfma_f32_16x16x32_bf16 v[104:107], v[228:231], v[108:111], v[104:107]
	v_mfma_f32_16x16x32_bf16 v[108:111], v[216:219], v[112:115], v[176:179]
	v_mfma_f32_16x16x32_bf16 v[112:115], v[224:227], v[112:115], v[180:183]
	v_mfma_f32_16x16x32_bf16 v[116:119], v[216:219], v[236:239], v[184:187]
	v_mfma_f32_16x16x32_bf16 v[120:123], v[224:227], v[236:239], v[120:123]
	v_mfma_f32_16x16x32_bf16 v[124:127], v[216:219], v[246:249], v[188:191]
	v_mfma_f32_16x16x32_bf16 v[128:131], v[224:227], v[246:249], v[128:131]
	v_mfma_f32_16x16x32_bf16 v[108:111], v[220:223], v[232:235], v[108:111]
	v_mfma_f32_16x16x32_bf16 v[112:115], v[228:231], v[232:235], v[112:115]
	v_mfma_f32_16x16x32_bf16 v[116:119], v[220:223], v[242:245], v[116:119]
	v_mfma_f32_16x16x32_bf16 v[120:123], v[228:231], v[242:245], v[120:123]
	v_mfma_f32_16x16x32_bf16 v[124:127], v[220:223], v[250:253], v[124:127]
	v_mfma_f32_16x16x32_bf16 v[128:131], v[228:231], v[250:253], v[128:131]
	s_setprio 0
	s_barrier
	s_andn2_b64 vcc, exec, s[66:67]
	s_cbranch_vccnz .LBB0_288
	s_add_u32 s52, s20, 0x200
	s_addc_u32 s53, s21, 0
	s_add_u32 s26, s26, 0x200
	s_addc_u32 s27, s27, 0
	s_mov_b32 s72, 4
	.p2align	6

.LBB0_427:
	s_add_u32 s8, s26, 0x100
	s_addc_u32 s9, s27, 0
	s_add_u32 s18, s20, 0x100
	s_addc_u32 s19, s21, 0
	s_and_b64 s[16:17], s[62:63], exec
	s_cselect_b32 s31, s51, s19
	s_cselect_b32 s30, s50, s18
	s_add_i32 s44, 0, 0x10000
	s_and_b64 s[16:17], s[62:63], exec
	s_cselect_b32 s19, s15, s9
	s_cselect_b32 s18, s14, s8
	s_add_i32 s8, 0, 0x14000
	v_add_u32_e32 v2, s44, v198
	v_add_u32_e32 v132, s8, v198
	ds_read_b128 v[4:7], v2
	ds_read_b128 v[8:11], v2 offset:1024
	ds_read_b128 v[12:15], v2 offset:2048
	ds_read_b128 v[16:19], v2 offset:3072
	ds_read_b128 v[20:23], v132
	ds_read_b128 v[24:27], v132 offset:1024
	ds_read_b128 v[28:31], v132 offset:2048
	ds_read_b128 v[32:35], v132 offset:3072
	s_add_u32 s16, s26, 0x80
	s_addc_u32 s17, s27, 0
	s_add_i32 s40, s84, 0x8000
	s_add_i32 s41, s84, 0xa000
	s_mov_b64 s[28:29], s[16:17]
	s_mov_b32 m0, s40
	s_add_u32 s16, s16, s52
	ds_read_b128 v[36:39], v199
	ds_read_b128 v[40:43], v199 offset:1024
	ds_read_b128 v[44:47], v199 offset:2048
	ds_read_b128 v[48:51], v199 offset:3072
	ds_read_b128 v[52:55], v199 offset:4096
	ds_read_b128 v[56:59], v199 offset:5120
	ds_read_b128 v[60:63], v199 offset:6144
	ds_read_b128 v[64:67], v199 offset:7168
	s_addc_u32 s17, s17, s53
	global_load_lds_dwordx4 v194, s[28:29]
	s_mov_b32 m0, s41
	s_add_i32 s42, s84, 0xc000
	global_load_lds_dwordx4 v195, s[28:29]
	s_mov_b32 m0, s42
	s_add_i32 s43, s84, 0xe000
	s_add_u32 s28, s30, 0x80
	global_load_lds_dwordx4 v194, s[16:17]
	s_mov_b32 m0, s43
	s_addc_u32 s29, s31, 0
	global_load_lds_dwordx4 v195, s[16:17]
	s_waitcnt vmcnt(8)
	s_waitcnt lgkmcnt(0)
	s_barrier
	s_setprio 1
	s_waitcnt lgkmcnt(0)
	v_mfma_f32_16x16x32_bf16 v[68:71], v[4:7], v[36:39], 0
	v_mfma_f32_16x16x32_bf16 v[72:75], v[12:15], v[36:39], 0
	v_mfma_f32_16x16x32_bf16 v[76:79], v[4:7], v[44:47], 0
	v_mfma_f32_16x16x32_bf16 v[80:83], v[12:15], v[44:47], 0
	v_mfma_f32_16x16x32_bf16 v[84:87], v[4:7], v[52:55], 0
	v_mfma_f32_16x16x32_bf16 v[88:91], v[12:15], v[52:55], 0
	v_mfma_f32_16x16x32_bf16 v[92:95], v[4:7], v[60:63], 0
	v_mfma_f32_16x16x32_bf16 v[96:99], v[12:15], v[60:63], 0
	v_mfma_f32_16x16x32_bf16 v[68:71], v[8:11], v[40:43], v[68:71]
	v_mfma_f32_16x16x32_bf16 v[72:75], v[16:19], v[40:43], v[72:75]
	v_mfma_f32_16x16x32_bf16 v[76:79], v[8:11], v[48:51], v[76:79]
	v_mfma_f32_16x16x32_bf16 v[80:83], v[16:19], v[48:51], v[80:83]
	v_mfma_f32_16x16x32_bf16 v[84:87], v[8:11], v[56:59], v[84:87]
	v_mfma_f32_16x16x32_bf16 v[88:91], v[16:19], v[56:59], v[88:91]
	v_mfma_f32_16x16x32_bf16 v[92:95], v[8:11], v[64:67], v[92:95]
	v_mfma_f32_16x16x32_bf16 v[96:99], v[16:19], v[64:67], v[96:99]
	s_setprio 0
	s_setprio 1
	v_mfma_f32_16x16x32_bf16 v[100:103], v[20:23], v[36:39], 0
	v_mfma_f32_16x16x32_bf16 v[36:39], v[28:31], v[36:39], 0
	v_mfma_f32_16x16x32_bf16 v[100:103], v[24:27], v[40:43], v[100:103]
	v_mfma_f32_16x16x32_bf16 v[40:43], v[32:35], v[40:43], v[36:39]
	v_mfma_f32_16x16x32_bf16 v[36:39], v[20:23], v[44:47], 0
	v_mfma_f32_16x16x32_bf16 v[104:107], v[24:27], v[48:51], v[36:39]
	v_mfma_f32_16x16x32_bf16 v[36:39], v[28:31], v[44:47], 0
	v_mfma_f32_16x16x32_bf16 v[48:51], v[32:35], v[48:51], v[36:39]
	v_mfma_f32_16x16x32_bf16 v[36:39], v[20:23], v[52:55], 0
	v_mfma_f32_16x16x32_bf16 v[108:111], v[24:27], v[56:59], v[36:39]
	v_mfma_f32_16x16x32_bf16 v[36:39], v[28:31], v[52:55], 0
	v_mfma_f32_16x16x32_bf16 v[56:59], v[32:35], v[56:59], v[36:39]
	v_mfma_f32_16x16x32_bf16 v[36:39], v[20:23], v[60:63], 0
	v_mfma_f32_16x16x32_bf16 v[112:115], v[24:27], v[64:67], v[36:39]
	v_mfma_f32_16x16x32_bf16 v[36:39], v[28:31], v[60:63], 0
	v_mfma_f32_16x16x32_bf16 v[64:67], v[32:35], v[64:67], v[36:39]
	s_setprio 0
	s_barrier
	s_add_i32 s44, s44, s82
	s_mov_b64 s[16:17], s[30:31]
	s_mov_b32 m0, s44
	s_add_i32 s45, s44, 0x2000
	s_nop 0
	ds_read_b128 v[36:39], v199 offset:16384
	ds_read_b128 v[44:47], v199 offset:17408
	ds_read_b128 v[52:55], v199 offset:18432
	ds_read_b128 v[60:63], v199 offset:19456
	ds_read_b128 v[116:119], v199 offset:20480
	ds_read_b128 v[120:123], v199 offset:21504
	ds_read_b128 v[124:127], v199 offset:22528
	ds_read_b128 v[128:131], v199 offset:23552
	s_nop 0
	global_load_lds_dwordx4 v201, s[16:17]
	s_mov_b32 m0, s45
	s_nop 0
	global_load_lds_dwordx4 v200, s[16:17]
	s_add_u32 s16, s30, s52
	s_addc_u32 s17, s31, s53
	s_add_i32 s30, s8, s82
	s_mov_b32 m0, s30
	s_add_i32 s31, s30, 0x2000
	s_nop 0
	global_load_lds_dwordx4 v201, s[16:17]
	s_mov_b32 m0, s31
	s_nop 0
	global_load_lds_dwordx4 v200, s[16:17]
	s_waitcnt vmcnt(6)
	s_waitcnt lgkmcnt(0)
	s_barrier
	s_setprio 1
	s_waitcnt lgkmcnt(0)
	v_mfma_f32_16x16x32_bf16 v[134:137], v[4:7], v[36:39], 0
	v_mfma_f32_16x16x32_bf16 v[144:147], v[4:7], v[52:55], 0
	v_mfma_f32_16x16x32_bf16 v[152:155], v[4:7], v[116:119], 0
	v_mfma_f32_16x16x32_bf16 v[4:7], v[4:7], v[124:127], 0
	v_mfma_f32_16x16x32_bf16 v[140:143], v[12:15], v[36:39], 0
	v_mfma_f32_16x16x32_bf16 v[148:151], v[12:15], v[52:55], 0
	v_mfma_f32_16x16x32_bf16 v[156:159], v[12:15], v[116:119], 0
	v_mfma_f32_16x16x32_bf16 v[160:163], v[8:11], v[128:131], v[4:7]
	v_mfma_f32_16x16x32_bf16 v[4:7], v[12:15], v[124:127], 0
	v_mfma_f32_16x16x32_bf16 v[136:139], v[8:11], v[44:47], v[134:137]
	v_mfma_f32_16x16x32_bf16 v[140:143], v[16:19], v[44:47], v[140:143]
	v_mfma_f32_16x16x32_bf16 v[144:147], v[8:11], v[60:63], v[144:147]
	v_mfma_f32_16x16x32_bf16 v[148:151], v[16:19], v[60:63], v[148:151]
	v_mfma_f32_16x16x32_bf16 v[152:155], v[8:11], v[120:123], v[152:155]
	v_mfma_f32_16x16x32_bf16 v[156:159], v[16:19], v[120:123], v[156:159]
	v_mfma_f32_16x16x32_bf16 v[164:167], v[16:19], v[128:131], v[4:7]
	s_setprio 0
	s_setprio 1
	v_mfma_f32_16x16x32_bf16 v[4:7], v[20:23], v[36:39], 0
	v_mfma_f32_16x16x32_bf16 v[168:171], v[24:27], v[44:47], v[4:7]
	v_mfma_f32_16x16x32_bf16 v[4:7], v[28:31], v[36:39], 0
	v_mfma_f32_16x16x32_bf16 v[172:175], v[32:35], v[44:47], v[4:7]
	v_mfma_f32_16x16x32_bf16 v[4:7], v[20:23], v[52:55], 0
	v_mfma_f32_16x16x32_bf16 v[176:179], v[24:27], v[60:63], v[4:7]
	v_mfma_f32_16x16x32_bf16 v[4:7], v[28:31], v[52:55], 0
	v_mfma_f32_16x16x32_bf16 v[180:183], v[32:35], v[60:63], v[4:7]
	v_mfma_f32_16x16x32_bf16 v[4:7], v[20:23], v[116:119], 0
	v_mfma_f32_16x16x32_bf16 v[184:187], v[24:27], v[120:123], v[4:7]
	v_mfma_f32_16x16x32_bf16 v[4:7], v[28:31], v[116:119], 0
	v_mfma_f32_16x16x32_bf16 v[120:123], v[32:35], v[120:123], v[4:7]
	v_mfma_f32_16x16x32_bf16 v[4:7], v[20:23], v[124:127], 0
	v_mfma_f32_16x16x32_bf16 v[188:191], v[24:27], v[128:131], v[4:7]
	v_mfma_f32_16x16x32_bf16 v[4:7], v[28:31], v[124:127], 0
	v_mfma_f32_16x16x32_bf16 v[128:131], v[32:35], v[128:131], v[4:7]
	s_setprio 0
	s_barrier
	s_add_i32 s46, 0, 0x18000
	s_add_i32 s8, 0, 0x1c000
	v_add_u32_e32 v133, s46, v198
	v_add_u32_e32 v134, s8, v198
	ds_read_b128 v[116:119], v133
	ds_read_b128 v[124:127], v133 offset:1024
	ds_read_b128 v[202:205], v133 offset:2048
	ds_read_b128 v[220:223], v133 offset:3072
	ds_read_b128 v[224:227], v134
	ds_read_b128 v[228:231], v134 offset:1024
	ds_read_b128 v[232:235], v134 offset:2048
	ds_read_b128 v[236:239], v134 offset:3072
	s_mov_b32 m0, s84
	s_mov_b64 s[16:17], s[18:19]
	ds_read_b128 v[44:47], v199 offset:32768
	ds_read_b128 v[52:55], v199 offset:33792
	ds_read_b128 v[60:63], v199 offset:34816
	ds_read_b128 v[242:245], v199 offset:35840
	ds_read_b128 v[246:249], v199 offset:36864
	ds_read_b128 v[250:253], v199 offset:37888
	ds_read_b128 v[206:209], v199 offset:38912
	ds_read_b128 v[216:219], v199 offset:39936
	s_nop 0
	global_load_lds_dwordx4 v194, s[16:17]
	s_mov_b32 m0, s85
	s_nop 0
	global_load_lds_dwordx4 v195, s[16:17]
	s_add_u32 s16, s18, s52
	s_addc_u32 s17, s19, s53
	s_mov_b32 m0, s86
	s_nop 0
	global_load_lds_dwordx4 v194, s[16:17]
	s_mov_b32 m0, s87
	s_nop 0
	global_load_lds_dwordx4 v195, s[16:17]
	s_waitcnt vmcnt(8)
	s_waitcnt lgkmcnt(0)
	s_barrier
	s_setprio 1
	s_waitcnt lgkmcnt(0)
	v_mfma_f32_16x16x32_bf16 v[4:7], v[116:119], v[44:47], v[68:71]
	v_mfma_f32_16x16x32_bf16 v[4:7], v[124:127], v[52:55], v[4:7]
	v_mfma_f32_16x16x32_bf16 v[8:11], v[202:205], v[44:47], v[72:75]
	v_mfma_f32_16x16x32_bf16 v[8:11], v[220:223], v[52:55], v[8:11]
	v_mfma_f32_16x16x32_bf16 v[12:15], v[116:119], v[60:63], v[76:79]
	v_mfma_f32_16x16x32_bf16 v[12:15], v[124:127], v[242:245], v[12:15]
	v_mfma_f32_16x16x32_bf16 v[16:19], v[202:205], v[60:63], v[80:83]
	v_mfma_f32_16x16x32_bf16 v[16:19], v[220:223], v[242:245], v[16:19]
	v_mfma_f32_16x16x32_bf16 v[20:23], v[116:119], v[246:249], v[84:87]
	v_mfma_f32_16x16x32_bf16 v[20:23], v[124:127], v[250:253], v[20:23]
	v_mfma_f32_16x16x32_bf16 v[24:27], v[202:205], v[246:249], v[88:91]
	v_mfma_f32_16x16x32_bf16 v[24:27], v[220:223], v[250:253], v[24:27]
	v_mfma_f32_16x16x32_bf16 v[28:31], v[116:119], v[206:209], v[92:95]
	v_mfma_f32_16x16x32_bf16 v[28:31], v[124:127], v[216:219], v[28:31]
	v_mfma_f32_16x16x32_bf16 v[32:35], v[202:205], v[206:209], v[96:99]
	v_mfma_f32_16x16x32_bf16 v[32:35], v[220:223], v[216:219], v[32:35]
	s_setprio 0
	s_setprio 1
	v_mfma_f32_16x16x32_bf16 v[36:39], v[224:227], v[44:47], v[100:103]
	v_mfma_f32_16x16x32_bf16 v[40:43], v[232:235], v[44:47], v[40:43]
	v_mfma_f32_16x16x32_bf16 v[36:39], v[228:231], v[52:55], v[36:39]
	v_mfma_f32_16x16x32_bf16 v[40:43], v[236:239], v[52:55], v[40:43]
	v_mfma_f32_16x16x32_bf16 v[44:47], v[224:227], v[60:63], v[104:107]
	v_mfma_f32_16x16x32_bf16 v[48:51], v[232:235], v[60:63], v[48:51]
	v_mfma_f32_16x16x32_bf16 v[52:55], v[224:227], v[246:249], v[108:111]
	v_mfma_f32_16x16x32_bf16 v[56:59], v[232:235], v[246:249], v[56:59]
	v_mfma_f32_16x16x32_bf16 v[60:63], v[224:227], v[206:209], v[112:115]
	v_mfma_f32_16x16x32_bf16 v[64:67], v[232:235], v[206:209], v[64:67]
	v_mfma_f32_16x16x32_bf16 v[44:47], v[228:231], v[242:245], v[44:47]
	v_mfma_f32_16x16x32_bf16 v[48:51], v[236:239], v[242:245], v[48:51]
	v_mfma_f32_16x16x32_bf16 v[52:55], v[228:231], v[250:253], v[52:55]
	v_mfma_f32_16x16x32_bf16 v[56:59], v[236:239], v[250:253], v[56:59]
	v_mfma_f32_16x16x32_bf16 v[60:63], v[228:231], v[216:219], v[60:63]
	v_mfma_f32_16x16x32_bf16 v[64:67], v[236:239], v[216:219], v[64:67]
	s_setprio 0
	s_barrier
	s_add_i32 s46, s46, s82
	s_mov_b64 s[16:17], s[28:29]
	s_mov_b32 m0, s46
	s_add_i32 s47, s46, 0x2000
	ds_read_b128 v[104:107], v199 offset:49152
	ds_read_b128 v[108:111], v199 offset:50176
	ds_read_b128 v[112:115], v199 offset:51200
	ds_read_b128 v[206:209], v199 offset:52224
	ds_read_b128 v[216:219], v199 offset:53248
	ds_read_b128 v[242:245], v199 offset:54272
	ds_read_b128 v[246:249], v199 offset:55296
	ds_read_b128 v[250:253], v199 offset:56320
	s_nop 0
	global_load_lds_dwordx4 v201, s[16:17]
	s_mov_b32 m0, s47
	s_nop 0
	global_load_lds_dwordx4 v200, s[16:17]
	s_add_u32 s16, s28, s52
	s_addc_u32 s17, s29, s53
	s_add_i32 s28, s8, s82
	s_mov_b32 m0, s28
	s_add_i32 s29, s28, 0x2000
	s_nop 0
	global_load_lds_dwordx4 v201, s[16:17]
	s_mov_b32 m0, s29
	s_nop 0
	global_load_lds_dwordx4 v200, s[16:17]
	s_waitcnt vmcnt(6)
	s_waitcnt lgkmcnt(0)
	s_barrier
	s_setprio 1
	s_waitcnt lgkmcnt(0)
	v_mfma_f32_16x16x32_bf16 v[68:71], v[116:119], v[104:107], v[136:139]
	v_mfma_f32_16x16x32_bf16 v[68:71], v[124:127], v[108:111], v[68:71]
	v_mfma_f32_16x16x32_bf16 v[72:75], v[202:205], v[104:107], v[140:143]
	v_mfma_f32_16x16x32_bf16 v[72:75], v[220:223], v[108:111], v[72:75]
	v_mfma_f32_16x16x32_bf16 v[76:79], v[116:119], v[112:115], v[144:147]
	v_mfma_f32_16x16x32_bf16 v[76:79], v[124:127], v[206:209], v[76:79]
	v_mfma_f32_16x16x32_bf16 v[80:83], v[202:205], v[112:115], v[148:151]
	v_mfma_f32_16x16x32_bf16 v[80:83], v[220:223], v[206:209], v[80:83]
	v_mfma_f32_16x16x32_bf16 v[84:87], v[116:119], v[216:219], v[152:155]
	v_mfma_f32_16x16x32_bf16 v[84:87], v[124:127], v[242:245], v[84:87]
	v_mfma_f32_16x16x32_bf16 v[88:91], v[202:205], v[216:219], v[156:159]
	v_mfma_f32_16x16x32_bf16 v[88:91], v[220:223], v[242:245], v[88:91]
	v_mfma_f32_16x16x32_bf16 v[92:95], v[116:119], v[246:249], v[160:163]
	v_mfma_f32_16x16x32_bf16 v[92:95], v[124:127], v[250:253], v[92:95]
	v_mfma_f32_16x16x32_bf16 v[96:99], v[202:205], v[246:249], v[164:167]
	v_mfma_f32_16x16x32_bf16 v[96:99], v[220:223], v[250:253], v[96:99]
	s_setprio 0
	s_setprio 1
	v_mfma_f32_16x16x32_bf16 v[100:103], v[224:227], v[104:107], v[168:171]
	v_mfma_f32_16x16x32_bf16 v[104:107], v[232:235], v[104:107], v[172:175]
	v_mfma_f32_16x16x32_bf16 v[100:103], v[228:231], v[108:111], v[100:103]
	v_mfma_f32_16x16x32_bf16 v[104:107], v[236:239], v[108:111], v[104:107]
	v_mfma_f32_16x16x32_bf16 v[108:111], v[224:227], v[112:115], v[176:179]
	v_mfma_f32_16x16x32_bf16 v[112:115], v[232:235], v[112:115], v[180:183]
	v_mfma_f32_16x16x32_bf16 v[116:119], v[224:227], v[216:219], v[184:187]
	v_mfma_f32_16x16x32_bf16 v[120:123], v[232:235], v[216:219], v[120:123]
	v_mfma_f32_16x16x32_bf16 v[124:127], v[224:227], v[246:249], v[188:191]
	v_mfma_f32_16x16x32_bf16 v[128:131], v[232:235], v[246:249], v[128:131]
	v_mfma_f32_16x16x32_bf16 v[108:111], v[228:231], v[206:209], v[108:111]
	v_mfma_f32_16x16x32_bf16 v[112:115], v[236:239], v[206:209], v[112:115]
	v_mfma_f32_16x16x32_bf16 v[116:119], v[228:231], v[242:245], v[116:119]
	v_mfma_f32_16x16x32_bf16 v[120:123], v[236:239], v[242:245], v[120:123]
	v_mfma_f32_16x16x32_bf16 v[124:127], v[228:231], v[250:253], v[124:127]
	v_mfma_f32_16x16x32_bf16 v[128:131], v[236:239], v[250:253], v[128:131]
	s_setprio 0
	s_barrier
	s_andn2_b64 vcc, exec, s[64:65]
	s_cbranch_vccnz .LBB0_431
	s_add_u32 s48, s20, 0x200
	s_addc_u32 s49, s21, 0
	s_add_u32 s26, s26, 0x200
	s_addc_u32 s27, s27, 0
	s_mov_b32 s66, 4
	.p2align	6

.LBB0_720:
	s_add_i32 s84, s84, 2
	s_and_b64 s[8:9], s[30:31], exec
	s_cselect_b32 s9, s39, s83
	s_cselect_b32 s8, s38, s82
	s_add_u32 s16, s28, 0x80
	v_mov_b32_e32 v197, v3
	v_mov_b32_e32 v201, v3
	v_mov_b32_e32 v199, v3
	s_addc_u32 s17, s29, 0
	s_setprio 0
	s_barrier
	s_add_i32 s28, 0, 0x18000
	s_add_i32 s29, 0, 0x1c000
	v_add_u32_e32 v144, s28, v204
	v_add_u32_e32 v160, s29, v204
	ds_read_b128 v[132:135], v144
	ds_read_b128 v[136:139], v144 offset:1024
	ds_read_b128 v[140:143], v144 offset:2048
	ds_read_b128 v[144:147], v144 offset:3072
	ds_read_b128 v[148:151], v160
	ds_read_b128 v[152:155], v160 offset:1024
	ds_read_b128 v[156:159], v160 offset:2048
	ds_read_b128 v[160:163], v160 offset:3072
	s_mov_b64 s[26:27], s[8:9]
	s_mov_b32 m0, s56
	s_waitcnt lgkmcnt(0)
	ds_read_b128 v[164:167], v205 offset:40960
	ds_read_b128 v[168:171], v205 offset:41984
	ds_read_b128 v[172:175], v205 offset:43008
	ds_read_b128 v[176:179], v205 offset:44032
	ds_read_b128 v[180:183], v205 offset:45056
	ds_read_b128 v[184:187], v205 offset:46080
	ds_read_b128 v[188:191], v205 offset:47104
	ds_read_b128 v[192:195], v205 offset:48128
	s_add_u32 s8, s8, s14
	v_lshl_add_u64 v[206:207], s[26:27], 0, v[2:3]
	global_load_lds_dwordx4 v[206:207], off
	v_lshl_add_u64 v[206:207], s[26:27], 0, v[196:197]
	s_mov_b32 m0, s61
	s_addc_u32 s9, s9, s15
	global_load_lds_dwordx4 v[206:207], off
	s_mov_b32 m0, s62
	v_lshl_add_u64 v[206:207], s[8:9], 0, v[2:3]
	global_load_lds_dwordx4 v[206:207], off
	v_lshl_add_u64 v[206:207], s[8:9], 0, v[196:197]
	s_mov_b32 m0, s63
	s_nop 0
	global_load_lds_dwordx4 v[206:207], off
	s_waitcnt vmcnt(8)
	s_waitcnt lgkmcnt(0)
	s_barrier
	s_setprio 1
	s_waitcnt lgkmcnt(0)
	v_mfma_f32_16x16x32_bf16 v[128:131], v[132:135], v[164:167], v[128:131]
	v_mfma_f32_16x16x32_bf16 v[128:131], v[136:139], v[168:171], v[128:131]
	v_mfma_f32_16x16x32_bf16 v[124:127], v[140:143], v[164:167], v[124:127]
	v_mfma_f32_16x16x32_bf16 v[124:127], v[144:147], v[168:171], v[124:127]
	v_mfma_f32_16x16x32_bf16 v[120:123], v[132:135], v[172:175], v[120:123]
	v_mfma_f32_16x16x32_bf16 v[120:123], v[136:139], v[176:179], v[120:123]
	v_mfma_f32_16x16x32_bf16 v[116:119], v[140:143], v[172:175], v[116:119]
	v_mfma_f32_16x16x32_bf16 v[116:119], v[144:147], v[176:179], v[116:119]
	v_mfma_f32_16x16x32_bf16 v[112:115], v[132:135], v[180:183], v[112:115]
	v_mfma_f32_16x16x32_bf16 v[112:115], v[136:139], v[184:187], v[112:115]
	v_mfma_f32_16x16x32_bf16 v[108:111], v[140:143], v[180:183], v[108:111]
	v_mfma_f32_16x16x32_bf16 v[108:111], v[144:147], v[184:187], v[108:111]
	v_mfma_f32_16x16x32_bf16 v[104:107], v[132:135], v[188:191], v[104:107]
	v_mfma_f32_16x16x32_bf16 v[104:107], v[136:139], v[192:195], v[104:107]
	v_mfma_f32_16x16x32_bf16 v[100:103], v[140:143], v[188:191], v[100:103]
	v_mfma_f32_16x16x32_bf16 v[100:103], v[144:147], v[192:195], v[100:103]
	s_setprio 0
	s_setprio 1
	v_mfma_f32_16x16x32_bf16 v[96:99], v[148:151], v[164:167], v[96:99]
	v_mfma_f32_16x16x32_bf16 v[96:99], v[152:155], v[168:171], v[96:99]
	v_mfma_f32_16x16x32_bf16 v[92:95], v[156:159], v[164:167], v[92:95]
	v_mfma_f32_16x16x32_bf16 v[92:95], v[160:163], v[168:171], v[92:95]
	v_mfma_f32_16x16x32_bf16 v[88:91], v[148:151], v[172:175], v[88:91]
	v_mfma_f32_16x16x32_bf16 v[88:91], v[152:155], v[176:179], v[88:91]
	v_mfma_f32_16x16x32_bf16 v[84:87], v[156:159], v[172:175], v[84:87]
	v_mfma_f32_16x16x32_bf16 v[84:87], v[160:163], v[176:179], v[84:87]
	v_mfma_f32_16x16x32_bf16 v[80:83], v[148:151], v[180:183], v[80:83]
	v_mfma_f32_16x16x32_bf16 v[80:83], v[152:155], v[184:187], v[80:83]
	v_mfma_f32_16x16x32_bf16 v[76:79], v[156:159], v[180:183], v[76:79]
	v_mfma_f32_16x16x32_bf16 v[76:79], v[160:163], v[184:187], v[76:79]
	v_mfma_f32_16x16x32_bf16 v[72:75], v[148:151], v[188:191], v[72:75]
	v_mfma_f32_16x16x32_bf16 v[72:75], v[152:155], v[192:195], v[72:75]
	v_mfma_f32_16x16x32_bf16 v[68:71], v[156:159], v[188:191], v[68:71]
	v_mfma_f32_16x16x32_bf16 v[68:71], v[160:163], v[192:195], v[68:71]
	s_setprio 0
	s_barrier
	s_mov_b64 s[8:9], s[16:17]
	s_add_i32 s26, s28, s55
	ds_read_b128 v[164:167], v205 offset:57344
	ds_read_b128 v[168:171], v205 offset:58368
	ds_read_b128 v[172:175], v205 offset:59392
	ds_read_b128 v[176:179], v205 offset:60416
	ds_read_b128 v[180:183], v205 offset:61440
	ds_read_b128 v[184:187], v205 offset:62464
	ds_read_b128 v[188:191], v205 offset:63488
	ds_read_b128 v[192:195], v205 offset:64512
	s_mov_b32 m0, s26
	v_lshl_add_u64 v[206:207], s[8:9], 0, v[200:201]
	global_load_lds_dwordx4 v[206:207], off
	s_add_i32 m0, s26, 0x2000
	v_lshl_add_u64 v[206:207], s[8:9], 0, v[198:199]
	s_add_u32 s8, s16, s14
	s_addc_u32 s9, s17, s15
	s_add_i32 s16, s29, s55
	global_load_lds_dwordx4 v[206:207], off
	s_mov_b32 m0, s16
	v_lshl_add_u64 v[206:207], s[8:9], 0, v[200:201]
	global_load_lds_dwordx4 v[206:207], off
	v_lshl_add_u64 v[206:207], s[8:9], 0, v[198:199]
	s_add_i32 m0, s16, 0x2000
	s_nop 0
	global_load_lds_dwordx4 v[206:207], off
	s_waitcnt vmcnt(6)
	s_waitcnt lgkmcnt(0)
	s_barrier
	s_setprio 1
	s_waitcnt lgkmcnt(0)
	v_mfma_f32_16x16x32_bf16 v[64:67], v[132:135], v[164:167], v[64:67]
	v_mfma_f32_16x16x32_bf16 v[64:67], v[136:139], v[168:171], v[64:67]
	v_mfma_f32_16x16x32_bf16 v[60:63], v[140:143], v[164:167], v[60:63]
	v_mfma_f32_16x16x32_bf16 v[60:63], v[144:147], v[168:171], v[60:63]
	v_mfma_f32_16x16x32_bf16 v[56:59], v[132:135], v[172:175], v[56:59]
	v_mfma_f32_16x16x32_bf16 v[56:59], v[136:139], v[176:179], v[56:59]
	v_mfma_f32_16x16x32_bf16 v[52:55], v[140:143], v[172:175], v[52:55]
	v_mfma_f32_16x16x32_bf16 v[52:55], v[144:147], v[176:179], v[52:55]
	v_mfma_f32_16x16x32_bf16 v[48:51], v[132:135], v[180:183], v[48:51]
	v_mfma_f32_16x16x32_bf16 v[48:51], v[136:139], v[184:187], v[48:51]
	v_mfma_f32_16x16x32_bf16 v[44:47], v[140:143], v[180:183], v[44:47]
	v_mfma_f32_16x16x32_bf16 v[44:47], v[144:147], v[184:187], v[44:47]
	v_mfma_f32_16x16x32_bf16 v[40:43], v[132:135], v[188:191], v[40:43]
	v_mfma_f32_16x16x32_bf16 v[40:43], v[136:139], v[192:195], v[40:43]
	v_mfma_f32_16x16x32_bf16 v[36:39], v[140:143], v[188:191], v[36:39]
	v_mfma_f32_16x16x32_bf16 v[36:39], v[144:147], v[192:195], v[36:39]
	s_setprio 0
	s_setprio 1
	v_mfma_f32_16x16x32_bf16 v[32:35], v[148:151], v[164:167], v[32:35]
	v_mfma_f32_16x16x32_bf16 v[32:35], v[152:155], v[168:171], v[32:35]
	v_mfma_f32_16x16x32_bf16 v[28:31], v[156:159], v[164:167], v[28:31]
	v_mfma_f32_16x16x32_bf16 v[28:31], v[160:163], v[168:171], v[28:31]
	v_mfma_f32_16x16x32_bf16 v[24:27], v[148:151], v[172:175], v[24:27]
	v_mfma_f32_16x16x32_bf16 v[24:27], v[152:155], v[176:179], v[24:27]
	v_mfma_f32_16x16x32_bf16 v[20:23], v[156:159], v[172:175], v[20:23]
	v_mfma_f32_16x16x32_bf16 v[20:23], v[160:163], v[176:179], v[20:23]
	v_mfma_f32_16x16x32_bf16 v[16:19], v[148:151], v[180:183], v[16:19]
	v_mfma_f32_16x16x32_bf16 v[16:19], v[152:155], v[184:187], v[16:19]
	v_mfma_f32_16x16x32_bf16 v[12:15], v[156:159], v[180:183], v[12:15]
	v_mfma_f32_16x16x32_bf16 v[12:15], v[160:163], v[184:187], v[12:15]
	v_mfma_f32_16x16x32_bf16 v[8:11], v[148:151], v[188:191], v[8:11]
	v_mfma_f32_16x16x32_bf16 v[8:11], v[152:155], v[192:195], v[8:11]
	v_mfma_f32_16x16x32_bf16 v[4:7], v[156:159], v[188:191], v[4:7]
	v_mfma_f32_16x16x32_bf16 v[4:7], v[160:163], v[192:195], v[4:7]
	s_setprio 0
	s_barrier
	s_add_u32 s80, s80, 0x100
	s_addc_u32 s81, s81, 0
	s_add_u32 s82, s82, 0x100
	s_addc_u32 s83, s83, 0
	s_cmp_ge_u32 s84, s47
	s_cbranch_scc1 .LBB0_737
	.p2align	6

.LBB0_760:
	s_add_i32 s80, s80, 2
	s_and_b64 s[8:9], s[30:31], exec
	s_cselect_b32 s9, s39, s79
	s_cselect_b32 s8, s38, s78
	s_add_u32 s16, s28, 0x80
	v_mov_b32_e32 v197, v3
	v_mov_b32_e32 v201, v3
	v_mov_b32_e32 v199, v3
	s_addc_u32 s17, s29, 0
	s_setprio 0
	s_barrier
	s_add_i32 s28, 0, 0x18000
	s_add_i32 s29, 0, 0x1c000
	v_add_u32_e32 v144, s28, v204
	v_add_u32_e32 v160, s29, v204
	ds_read_b128 v[132:135], v144
	ds_read_b128 v[136:139], v144 offset:1024
	ds_read_b128 v[140:143], v144 offset:2048
	ds_read_b128 v[144:147], v144 offset:3072
	ds_read_b128 v[148:151], v160
	ds_read_b128 v[152:155], v160 offset:1024
	ds_read_b128 v[156:159], v160 offset:2048
	ds_read_b128 v[160:163], v160 offset:3072
	s_mov_b64 s[26:27], s[8:9]
	s_mov_b32 m0, s56
	s_waitcnt lgkmcnt(0)
	ds_read_b128 v[164:167], v205 offset:32768
	ds_read_b128 v[168:171], v205 offset:33792
	ds_read_b128 v[172:175], v205 offset:34816
	ds_read_b128 v[176:179], v205 offset:35840
	ds_read_b128 v[180:183], v205 offset:36864
	ds_read_b128 v[184:187], v205 offset:37888
	ds_read_b128 v[188:191], v205 offset:38912
	ds_read_b128 v[192:195], v205 offset:39936
	s_add_u32 s8, s8, s14
	v_lshl_add_u64 v[206:207], s[26:27], 0, v[2:3]
	global_load_lds_dwordx4 v[206:207], off
	v_lshl_add_u64 v[206:207], s[26:27], 0, v[196:197]
	s_mov_b32 m0, s61
	s_addc_u32 s9, s9, s15
	global_load_lds_dwordx4 v[206:207], off
	s_mov_b32 m0, s62
	v_lshl_add_u64 v[206:207], s[8:9], 0, v[2:3]
	global_load_lds_dwordx4 v[206:207], off
	v_lshl_add_u64 v[206:207], s[8:9], 0, v[196:197]
	s_mov_b32 m0, s63
	s_nop 0
	global_load_lds_dwordx4 v[206:207], off
	s_waitcnt vmcnt(8)
	s_waitcnt lgkmcnt(0)
	s_barrier
	s_setprio 1
	s_waitcnt lgkmcnt(0)
	v_mfma_f32_16x16x32_bf16 v[128:131], v[132:135], v[164:167], v[128:131]
	v_mfma_f32_16x16x32_bf16 v[128:131], v[136:139], v[168:171], v[128:131]
	v_mfma_f32_16x16x32_bf16 v[124:127], v[140:143], v[164:167], v[124:127]
	v_mfma_f32_16x16x32_bf16 v[124:127], v[144:147], v[168:171], v[124:127]
	v_mfma_f32_16x16x32_bf16 v[120:123], v[132:135], v[172:175], v[120:123]
	v_mfma_f32_16x16x32_bf16 v[120:123], v[136:139], v[176:179], v[120:123]
	v_mfma_f32_16x16x32_bf16 v[116:119], v[140:143], v[172:175], v[116:119]
	v_mfma_f32_16x16x32_bf16 v[116:119], v[144:147], v[176:179], v[116:119]
	v_mfma_f32_16x16x32_bf16 v[112:115], v[132:135], v[180:183], v[112:115]
	v_mfma_f32_16x16x32_bf16 v[112:115], v[136:139], v[184:187], v[112:115]
	v_mfma_f32_16x16x32_bf16 v[108:111], v[140:143], v[180:183], v[108:111]
	v_mfma_f32_16x16x32_bf16 v[108:111], v[144:147], v[184:187], v[108:111]
	v_mfma_f32_16x16x32_bf16 v[104:107], v[132:135], v[188:191], v[104:107]
	v_mfma_f32_16x16x32_bf16 v[104:107], v[136:139], v[192:195], v[104:107]
	v_mfma_f32_16x16x32_bf16 v[100:103], v[140:143], v[188:191], v[100:103]
	v_mfma_f32_16x16x32_bf16 v[100:103], v[144:147], v[192:195], v[100:103]
	s_setprio 0
	s_setprio 1
	v_mfma_f32_16x16x32_bf16 v[96:99], v[148:151], v[164:167], v[96:99]
	v_mfma_f32_16x16x32_bf16 v[96:99], v[152:155], v[168:171], v[96:99]
	v_mfma_f32_16x16x32_bf16 v[92:95], v[156:159], v[164:167], v[92:95]
	v_mfma_f32_16x16x32_bf16 v[92:95], v[160:163], v[168:171], v[92:95]
	v_mfma_f32_16x16x32_bf16 v[88:91], v[148:151], v[172:175], v[88:91]
	v_mfma_f32_16x16x32_bf16 v[88:91], v[152:155], v[176:179], v[88:91]
	v_mfma_f32_16x16x32_bf16 v[84:87], v[156:159], v[172:175], v[84:87]
	v_mfma_f32_16x16x32_bf16 v[84:87], v[160:163], v[176:179], v[84:87]
	v_mfma_f32_16x16x32_bf16 v[80:83], v[148:151], v[180:183], v[80:83]
	v_mfma_f32_16x16x32_bf16 v[80:83], v[152:155], v[184:187], v[80:83]
	v_mfma_f32_16x16x32_bf16 v[76:79], v[156:159], v[180:183], v[76:79]
	v_mfma_f32_16x16x32_bf16 v[76:79], v[160:163], v[184:187], v[76:79]
	v_mfma_f32_16x16x32_bf16 v[72:75], v[148:151], v[188:191], v[72:75]
	v_mfma_f32_16x16x32_bf16 v[72:75], v[152:155], v[192:195], v[72:75]
	v_mfma_f32_16x16x32_bf16 v[68:71], v[156:159], v[188:191], v[68:71]
	v_mfma_f32_16x16x32_bf16 v[68:71], v[160:163], v[192:195], v[68:71]
	s_setprio 0
	s_barrier
	s_mov_b64 s[8:9], s[16:17]
	s_add_i32 s26, s28, s55
	ds_read_b128 v[164:167], v205 offset:49152
	ds_read_b128 v[168:171], v205 offset:50176
	ds_read_b128 v[172:175], v205 offset:51200
	ds_read_b128 v[176:179], v205 offset:52224
	ds_read_b128 v[180:183], v205 offset:53248
	ds_read_b128 v[184:187], v205 offset:54272
	ds_read_b128 v[188:191], v205 offset:55296
	ds_read_b128 v[192:195], v205 offset:56320
	s_mov_b32 m0, s26
	v_lshl_add_u64 v[206:207], s[8:9], 0, v[200:201]
	global_load_lds_dwordx4 v[206:207], off
	s_add_i32 m0, s26, 0x2000
	v_lshl_add_u64 v[206:207], s[8:9], 0, v[198:199]
	s_add_u32 s8, s16, s14
	s_addc_u32 s9, s17, s15
	s_add_i32 s16, s29, s55
	global_load_lds_dwordx4 v[206:207], off
	s_mov_b32 m0, s16
	v_lshl_add_u64 v[206:207], s[8:9], 0, v[200:201]
	global_load_lds_dwordx4 v[206:207], off
	v_lshl_add_u64 v[206:207], s[8:9], 0, v[198:199]
	s_add_i32 m0, s16, 0x2000
	s_nop 0
	global_load_lds_dwordx4 v[206:207], off
	s_waitcnt vmcnt(6)
	s_waitcnt lgkmcnt(0)
	s_barrier
	s_setprio 1
	s_waitcnt lgkmcnt(0)
	v_mfma_f32_16x16x32_bf16 v[64:67], v[132:135], v[164:167], v[64:67]
	v_mfma_f32_16x16x32_bf16 v[64:67], v[136:139], v[168:171], v[64:67]
	v_mfma_f32_16x16x32_bf16 v[60:63], v[140:143], v[164:167], v[60:63]
	v_mfma_f32_16x16x32_bf16 v[60:63], v[144:147], v[168:171], v[60:63]
	v_mfma_f32_16x16x32_bf16 v[56:59], v[132:135], v[172:175], v[56:59]
	v_mfma_f32_16x16x32_bf16 v[56:59], v[136:139], v[176:179], v[56:59]
	v_mfma_f32_16x16x32_bf16 v[52:55], v[140:143], v[172:175], v[52:55]
	v_mfma_f32_16x16x32_bf16 v[52:55], v[144:147], v[176:179], v[52:55]
	v_mfma_f32_16x16x32_bf16 v[48:51], v[132:135], v[180:183], v[48:51]
	v_mfma_f32_16x16x32_bf16 v[48:51], v[136:139], v[184:187], v[48:51]
	v_mfma_f32_16x16x32_bf16 v[44:47], v[140:143], v[180:183], v[44:47]
	v_mfma_f32_16x16x32_bf16 v[44:47], v[144:147], v[184:187], v[44:47]
	v_mfma_f32_16x16x32_bf16 v[40:43], v[132:135], v[188:191], v[40:43]
	v_mfma_f32_16x16x32_bf16 v[40:43], v[136:139], v[192:195], v[40:43]
	v_mfma_f32_16x16x32_bf16 v[36:39], v[140:143], v[188:191], v[36:39]
	v_mfma_f32_16x16x32_bf16 v[36:39], v[144:147], v[192:195], v[36:39]
	s_setprio 0
	s_setprio 1
	v_mfma_f32_16x16x32_bf16 v[32:35], v[148:151], v[164:167], v[32:35]
	v_mfma_f32_16x16x32_bf16 v[32:35], v[152:155], v[168:171], v[32:35]
	v_mfma_f32_16x16x32_bf16 v[28:31], v[156:159], v[164:167], v[28:31]
	v_mfma_f32_16x16x32_bf16 v[28:31], v[160:163], v[168:171], v[28:31]
	v_mfma_f32_16x16x32_bf16 v[24:27], v[148:151], v[172:175], v[24:27]
	v_mfma_f32_16x16x32_bf16 v[24:27], v[152:155], v[176:179], v[24:27]
	v_mfma_f32_16x16x32_bf16 v[20:23], v[156:159], v[172:175], v[20:23]
	v_mfma_f32_16x16x32_bf16 v[20:23], v[160:163], v[176:179], v[20:23]
	v_mfma_f32_16x16x32_bf16 v[16:19], v[148:151], v[180:183], v[16:19]
	v_mfma_f32_16x16x32_bf16 v[16:19], v[152:155], v[184:187], v[16:19]
	v_mfma_f32_16x16x32_bf16 v[12:15], v[156:159], v[180:183], v[12:15]
	v_mfma_f32_16x16x32_bf16 v[12:15], v[160:163], v[184:187], v[12:15]
	v_mfma_f32_16x16x32_bf16 v[8:11], v[148:151], v[188:191], v[8:11]
	v_mfma_f32_16x16x32_bf16 v[8:11], v[152:155], v[192:195], v[8:11]
	v_mfma_f32_16x16x32_bf16 v[4:7], v[156:159], v[188:191], v[4:7]
	v_mfma_f32_16x16x32_bf16 v[4:7], v[160:163], v[192:195], v[4:7]
	s_setprio 0
	s_barrier
	s_add_u32 s76, s76, 0x100
	s_addc_u32 s77, s77, 0
	s_add_u32 s78, s78, 0x100
	s_addc_u32 s79, s79, 0
	s_cmp_ge_u32 s80, s47
	s_cbranch_scc1 .LBB0_777
	.p2align	6

.LBB0_853:
	s_add_u32 s16, s26, 0x100
	s_addc_u32 s17, s27, 0
	s_add_u32 s18, s20, 0x100
	s_addc_u32 s19, s21, 0
	s_and_b64 s[8:9], s[52:53], exec
	s_cselect_b32 s31, s41, s19
	s_cselect_b32 s30, s40, s18
	s_add_i32 s84, 0, 0x10000
	s_and_b64 s[8:9], s[52:53], exec
	s_cselect_b32 s19, s59, s17
	s_cselect_b32 s18, s58, s16
	s_add_i32 s86, 0, 0x14000
	v_add_u32_e32 v132, s84, v245
	v_add_u32_e32 v133, s86, v245
	ds_read_b128 v[4:7], v132
	ds_read_b128 v[8:11], v132 offset:1024
	ds_read_b128 v[12:15], v132 offset:2048
	ds_read_b128 v[16:19], v132 offset:3072
	ds_read_b128 v[20:23], v133
	ds_read_b128 v[24:27], v133 offset:1024
	ds_read_b128 v[28:31], v133 offset:2048
	ds_read_b128 v[32:35], v133 offset:3072
	s_add_u32 s8, s26, 0x80
	s_addc_u32 s9, s27, 0
	s_add_i32 s80, s7, 0x8000
	s_add_i32 s81, s7, 0xa000
	s_mov_b64 s[16:17], s[8:9]
	s_mov_b32 m0, s80
	s_add_u32 s8, s8, s42
	ds_read_b128 v[36:39], v246 offset:8192
	ds_read_b128 v[40:43], v246 offset:9216
	ds_read_b128 v[44:47], v246 offset:10240
	ds_read_b128 v[48:51], v246 offset:11264
	ds_read_b128 v[52:55], v246 offset:12288
	ds_read_b128 v[56:59], v246 offset:13312
	ds_read_b128 v[60:63], v246 offset:14336
	ds_read_b128 v[64:67], v246 offset:15360
	s_addc_u32 s9, s9, s43
	global_load_lds_dwordx4 v242, s[16:17]
	s_mov_b32 m0, s81
	s_add_i32 s82, s7, 0xc000
	global_load_lds_dwordx4 v2, s[16:17]
	s_mov_b32 m0, s82
	s_add_i32 s83, s7, 0xe000
	s_add_u32 s28, s30, 0x80
	global_load_lds_dwordx4 v242, s[8:9]
	s_mov_b32 m0, s83
	s_addc_u32 s29, s31, 0
	global_load_lds_dwordx4 v2, s[8:9]
	s_waitcnt vmcnt(8)
	s_waitcnt lgkmcnt(0)
	s_barrier
	s_setprio 1
	s_waitcnt lgkmcnt(0)
	v_mfma_f32_16x16x32_bf16 v[68:71], v[4:7], v[36:39], 0
	v_mfma_f32_16x16x32_bf16 v[72:75], v[12:15], v[36:39], 0
	v_mfma_f32_16x16x32_bf16 v[76:79], v[4:7], v[44:47], 0
	v_mfma_f32_16x16x32_bf16 v[80:83], v[12:15], v[44:47], 0
	v_mfma_f32_16x16x32_bf16 v[84:87], v[4:7], v[52:55], 0
	v_mfma_f32_16x16x32_bf16 v[88:91], v[12:15], v[52:55], 0
	v_mfma_f32_16x16x32_bf16 v[92:95], v[4:7], v[60:63], 0
	v_mfma_f32_16x16x32_bf16 v[96:99], v[12:15], v[60:63], 0
	v_mfma_f32_16x16x32_bf16 v[68:71], v[8:11], v[40:43], v[68:71]
	v_mfma_f32_16x16x32_bf16 v[72:75], v[16:19], v[40:43], v[72:75]
	v_mfma_f32_16x16x32_bf16 v[76:79], v[8:11], v[48:51], v[76:79]
	v_mfma_f32_16x16x32_bf16 v[80:83], v[16:19], v[48:51], v[80:83]
	v_mfma_f32_16x16x32_bf16 v[84:87], v[8:11], v[56:59], v[84:87]
	v_mfma_f32_16x16x32_bf16 v[88:91], v[16:19], v[56:59], v[88:91]
	v_mfma_f32_16x16x32_bf16 v[92:95], v[8:11], v[64:67], v[92:95]
	v_mfma_f32_16x16x32_bf16 v[96:99], v[16:19], v[64:67], v[96:99]
	s_setprio 0
	s_setprio 1
	v_mfma_f32_16x16x32_bf16 v[100:103], v[20:23], v[36:39], 0
	v_mfma_f32_16x16x32_bf16 v[36:39], v[28:31], v[36:39], 0
	v_mfma_f32_16x16x32_bf16 v[100:103], v[24:27], v[40:43], v[100:103]
	v_mfma_f32_16x16x32_bf16 v[40:43], v[32:35], v[40:43], v[36:39]
	v_mfma_f32_16x16x32_bf16 v[36:39], v[20:23], v[44:47], 0
	v_mfma_f32_16x16x32_bf16 v[104:107], v[24:27], v[48:51], v[36:39]
	v_mfma_f32_16x16x32_bf16 v[36:39], v[28:31], v[44:47], 0
	v_mfma_f32_16x16x32_bf16 v[48:51], v[32:35], v[48:51], v[36:39]
	v_mfma_f32_16x16x32_bf16 v[36:39], v[20:23], v[52:55], 0
	v_mfma_f32_16x16x32_bf16 v[108:111], v[24:27], v[56:59], v[36:39]
	v_mfma_f32_16x16x32_bf16 v[36:39], v[28:31], v[52:55], 0
	v_mfma_f32_16x16x32_bf16 v[56:59], v[32:35], v[56:59], v[36:39]
	v_mfma_f32_16x16x32_bf16 v[36:39], v[20:23], v[60:63], 0
	v_mfma_f32_16x16x32_bf16 v[112:115], v[24:27], v[64:67], v[36:39]
	v_mfma_f32_16x16x32_bf16 v[36:39], v[28:31], v[60:63], 0
	v_mfma_f32_16x16x32_bf16 v[64:67], v[32:35], v[64:67], v[36:39]
	s_setprio 0
	s_barrier
	s_add_i32 s84, s84, s6
	s_mov_b64 s[8:9], s[30:31]
	s_mov_b32 m0, s84
	s_add_i32 s85, s84, 0x2000
	s_nop 0
	ds_read_b128 v[36:39], v246 offset:24576
	ds_read_b128 v[44:47], v246 offset:25600
	ds_read_b128 v[52:55], v246 offset:26624
	ds_read_b128 v[60:63], v246 offset:27648
	ds_read_b128 v[116:119], v246 offset:28672
	ds_read_b128 v[120:123], v246 offset:29696
	ds_read_b128 v[124:127], v246 offset:30720
	ds_read_b128 v[128:131], v246 offset:31744
	s_nop 0
	global_load_lds_dwordx4 v248, s[8:9]
	s_mov_b32 m0, s85
	s_nop 0
	global_load_lds_dwordx4 v247, s[8:9]
	s_add_u32 s8, s30, s42
	s_addc_u32 s9, s31, s43
	s_add_i32 s30, s86, s6
	s_mov_b32 m0, s30
	s_add_i32 s31, s30, 0x2000
	s_nop 0
	global_load_lds_dwordx4 v248, s[8:9]
	s_mov_b32 m0, s31
	s_nop 0
	global_load_lds_dwordx4 v247, s[8:9]
	s_waitcnt vmcnt(6)
	s_waitcnt lgkmcnt(0)
	s_barrier
	s_setprio 1
	s_waitcnt lgkmcnt(0)
	v_mfma_f32_16x16x32_bf16 v[134:137], v[4:7], v[36:39], 0
	v_mfma_f32_16x16x32_bf16 v[144:147], v[4:7], v[52:55], 0
	v_mfma_f32_16x16x32_bf16 v[152:155], v[4:7], v[116:119], 0
	v_mfma_f32_16x16x32_bf16 v[4:7], v[4:7], v[124:127], 0
	v_mfma_f32_16x16x32_bf16 v[140:143], v[12:15], v[36:39], 0
	v_mfma_f32_16x16x32_bf16 v[148:151], v[12:15], v[52:55], 0
	v_mfma_f32_16x16x32_bf16 v[156:159], v[12:15], v[116:119], 0
	v_mfma_f32_16x16x32_bf16 v[160:163], v[8:11], v[128:131], v[4:7]
	v_mfma_f32_16x16x32_bf16 v[4:7], v[12:15], v[124:127], 0
	v_mfma_f32_16x16x32_bf16 v[136:139], v[8:11], v[44:47], v[134:137]
	v_mfma_f32_16x16x32_bf16 v[140:143], v[16:19], v[44:47], v[140:143]
	v_mfma_f32_16x16x32_bf16 v[144:147], v[8:11], v[60:63], v[144:147]
	v_mfma_f32_16x16x32_bf16 v[148:151], v[16:19], v[60:63], v[148:151]
	v_mfma_f32_16x16x32_bf16 v[152:155], v[8:11], v[120:123], v[152:155]
	v_mfma_f32_16x16x32_bf16 v[156:159], v[16:19], v[120:123], v[156:159]
	v_mfma_f32_16x16x32_bf16 v[164:167], v[16:19], v[128:131], v[4:7]
	s_setprio 0
	s_setprio 1
	v_mfma_f32_16x16x32_bf16 v[4:7], v[20:23], v[36:39], 0
	v_mfma_f32_16x16x32_bf16 v[168:171], v[24:27], v[44:47], v[4:7]
	v_mfma_f32_16x16x32_bf16 v[4:7], v[28:31], v[36:39], 0
	v_mfma_f32_16x16x32_bf16 v[172:175], v[32:35], v[44:47], v[4:7]
	v_mfma_f32_16x16x32_bf16 v[4:7], v[20:23], v[52:55], 0
	v_mfma_f32_16x16x32_bf16 v[176:179], v[24:27], v[60:63], v[4:7]
	v_mfma_f32_16x16x32_bf16 v[4:7], v[28:31], v[52:55], 0
	v_mfma_f32_16x16x32_bf16 v[180:183], v[32:35], v[60:63], v[4:7]
	v_mfma_f32_16x16x32_bf16 v[4:7], v[20:23], v[116:119], 0
	v_mfma_f32_16x16x32_bf16 v[184:187], v[24:27], v[120:123], v[4:7]
	v_mfma_f32_16x16x32_bf16 v[4:7], v[28:31], v[116:119], 0
	v_mfma_f32_16x16x32_bf16 v[120:123], v[32:35], v[120:123], v[4:7]
	v_mfma_f32_16x16x32_bf16 v[4:7], v[20:23], v[124:127], 0
	v_mfma_f32_16x16x32_bf16 v[188:191], v[24:27], v[128:131], v[4:7]
	v_mfma_f32_16x16x32_bf16 v[4:7], v[28:31], v[124:127], 0
	v_mfma_f32_16x16x32_bf16 v[128:131], v[32:35], v[128:131], v[4:7]
	s_setprio 0
	s_barrier
	s_add_i32 s86, 0, 0x18000
	s_add_i32 s16, 0, 0x1c000
	v_add_u32_e32 v134, s86, v245
	v_add_u32_e32 v135, s16, v245
	ds_read_b128 v[116:119], v134
	ds_read_b128 v[124:127], v134 offset:1024
	ds_read_b128 v[192:195], v134 offset:2048
	ds_read_b128 v[196:199], v134 offset:3072
	ds_read_b128 v[200:203], v135
	ds_read_b128 v[204:207], v135 offset:1024
	ds_read_b128 v[216:219], v135 offset:2048
	ds_read_b128 v[220:223], v135 offset:3072
	s_mov_b32 m0, s7
	s_mov_b64 s[8:9], s[18:19]
	ds_read_b128 v[44:47], v246 offset:40960
	ds_read_b128 v[52:55], v246 offset:41984
	ds_read_b128 v[60:63], v246 offset:43008
	ds_read_b128 v[224:227], v246 offset:44032
	ds_read_b128 v[228:231], v246 offset:45056
	ds_read_b128 v[232:235], v246 offset:46080
	ds_read_b128 v[236:239], v246 offset:47104
	ds_read_b128 v[250:253], v246 offset:48128
	s_nop 0
	global_load_lds_dwordx4 v242, s[8:9]
	s_mov_b32 m0, s69
	s_nop 0
	global_load_lds_dwordx4 v2, s[8:9]
	s_add_u32 s8, s18, s42
	s_addc_u32 s9, s19, s43
	s_mov_b32 m0, s72
	s_nop 0
	global_load_lds_dwordx4 v242, s[8:9]
	s_mov_b32 m0, s73
	s_nop 0
	global_load_lds_dwordx4 v2, s[8:9]
	s_waitcnt vmcnt(8)
	s_waitcnt lgkmcnt(0)
	s_barrier
	s_setprio 1
	s_waitcnt lgkmcnt(0)
	v_mfma_f32_16x16x32_bf16 v[4:7], v[116:119], v[44:47], v[68:71]
	v_mfma_f32_16x16x32_bf16 v[4:7], v[124:127], v[52:55], v[4:7]
	v_mfma_f32_16x16x32_bf16 v[8:11], v[192:195], v[44:47], v[72:75]
	v_mfma_f32_16x16x32_bf16 v[8:11], v[196:199], v[52:55], v[8:11]
	v_mfma_f32_16x16x32_bf16 v[12:15], v[116:119], v[60:63], v[76:79]
	v_mfma_f32_16x16x32_bf16 v[12:15], v[124:127], v[224:227], v[12:15]
	v_mfma_f32_16x16x32_bf16 v[16:19], v[192:195], v[60:63], v[80:83]
	v_mfma_f32_16x16x32_bf16 v[16:19], v[196:199], v[224:227], v[16:19]
	v_mfma_f32_16x16x32_bf16 v[20:23], v[116:119], v[228:231], v[84:87]
	v_mfma_f32_16x16x32_bf16 v[20:23], v[124:127], v[232:235], v[20:23]
	v_mfma_f32_16x16x32_bf16 v[24:27], v[192:195], v[228:231], v[88:91]
	v_mfma_f32_16x16x32_bf16 v[24:27], v[196:199], v[232:235], v[24:27]
	v_mfma_f32_16x16x32_bf16 v[28:31], v[116:119], v[236:239], v[92:95]
	v_mfma_f32_16x16x32_bf16 v[28:31], v[124:127], v[250:253], v[28:31]
	v_mfma_f32_16x16x32_bf16 v[32:35], v[192:195], v[236:239], v[96:99]
	v_mfma_f32_16x16x32_bf16 v[32:35], v[196:199], v[250:253], v[32:35]
	s_setprio 0
	s_setprio 1
	v_mfma_f32_16x16x32_bf16 v[36:39], v[200:203], v[44:47], v[100:103]
	v_mfma_f32_16x16x32_bf16 v[40:43], v[216:219], v[44:47], v[40:43]
	v_mfma_f32_16x16x32_bf16 v[36:39], v[204:207], v[52:55], v[36:39]
	v_mfma_f32_16x16x32_bf16 v[40:43], v[220:223], v[52:55], v[40:43]
	v_mfma_f32_16x16x32_bf16 v[44:47], v[200:203], v[60:63], v[104:107]
	v_mfma_f32_16x16x32_bf16 v[48:51], v[216:219], v[60:63], v[48:51]
	v_mfma_f32_16x16x32_bf16 v[52:55], v[200:203], v[228:231], v[108:111]
	v_mfma_f32_16x16x32_bf16 v[56:59], v[216:219], v[228:231], v[56:59]
	v_mfma_f32_16x16x32_bf16 v[60:63], v[200:203], v[236:239], v[112:115]
	v_mfma_f32_16x16x32_bf16 v[64:67], v[216:219], v[236:239], v[64:67]
	v_mfma_f32_16x16x32_bf16 v[44:47], v[204:207], v[224:227], v[44:47]
	v_mfma_f32_16x16x32_bf16 v[48:51], v[220:223], v[224:227], v[48:51]
	v_mfma_f32_16x16x32_bf16 v[52:55], v[204:207], v[232:235], v[52:55]
	v_mfma_f32_16x16x32_bf16 v[56:59], v[220:223], v[232:235], v[56:59]
	v_mfma_f32_16x16x32_bf16 v[60:63], v[204:207], v[250:253], v[60:63]
	v_mfma_f32_16x16x32_bf16 v[64:67], v[220:223], v[250:253], v[64:67]
	s_setprio 0
	s_barrier
	s_add_i32 s86, s86, s6
	s_mov_b64 s[8:9], s[28:29]
	s_mov_b32 m0, s86
	s_add_i32 s87, s86, 0x2000
	ds_read_b128 v[104:107], v246 offset:57344
	ds_read_b128 v[108:111], v246 offset:58368
	ds_read_b128 v[112:115], v246 offset:59392
	ds_read_b128 v[224:227], v246 offset:60416
	ds_read_b128 v[228:231], v246 offset:61440
	ds_read_b128 v[232:235], v246 offset:62464
	ds_read_b128 v[236:239], v246 offset:63488
	ds_read_b128 v[250:253], v246 offset:64512
	s_nop 0
	global_load_lds_dwordx4 v248, s[8:9]
	s_mov_b32 m0, s87
	s_nop 0
	global_load_lds_dwordx4 v247, s[8:9]
	s_add_u32 s8, s28, s42
	s_addc_u32 s9, s29, s43
	s_add_i32 s28, s16, s6
	s_mov_b32 m0, s28
	s_add_i32 s29, s28, 0x2000
	s_nop 0
	global_load_lds_dwordx4 v248, s[8:9]
	s_mov_b32 m0, s29
	s_nop 0
	global_load_lds_dwordx4 v247, s[8:9]
	s_waitcnt vmcnt(6)
	s_waitcnt lgkmcnt(0)
	s_barrier
	s_setprio 1
	s_waitcnt lgkmcnt(0)
	v_mfma_f32_16x16x32_bf16 v[68:71], v[116:119], v[104:107], v[136:139]
	v_mfma_f32_16x16x32_bf16 v[68:71], v[124:127], v[108:111], v[68:71]
	v_mfma_f32_16x16x32_bf16 v[72:75], v[192:195], v[104:107], v[140:143]
	v_mfma_f32_16x16x32_bf16 v[72:75], v[196:199], v[108:111], v[72:75]
	v_mfma_f32_16x16x32_bf16 v[76:79], v[116:119], v[112:115], v[144:147]
	v_mfma_f32_16x16x32_bf16 v[76:79], v[124:127], v[224:227], v[76:79]
	v_mfma_f32_16x16x32_bf16 v[80:83], v[192:195], v[112:115], v[148:151]
	v_mfma_f32_16x16x32_bf16 v[80:83], v[196:199], v[224:227], v[80:83]
	v_mfma_f32_16x16x32_bf16 v[84:87], v[116:119], v[228:231], v[152:155]
	v_mfma_f32_16x16x32_bf16 v[84:87], v[124:127], v[232:235], v[84:87]
	v_mfma_f32_16x16x32_bf16 v[88:91], v[192:195], v[228:231], v[156:159]
	v_mfma_f32_16x16x32_bf16 v[88:91], v[196:199], v[232:235], v[88:91]
	v_mfma_f32_16x16x32_bf16 v[92:95], v[116:119], v[236:239], v[160:163]
	v_mfma_f32_16x16x32_bf16 v[92:95], v[124:127], v[250:253], v[92:95]
	v_mfma_f32_16x16x32_bf16 v[96:99], v[192:195], v[236:239], v[164:167]
	v_mfma_f32_16x16x32_bf16 v[96:99], v[196:199], v[250:253], v[96:99]
	s_setprio 0
	s_setprio 1
	v_mfma_f32_16x16x32_bf16 v[100:103], v[200:203], v[104:107], v[168:171]
	v_mfma_f32_16x16x32_bf16 v[104:107], v[216:219], v[104:107], v[172:175]
	v_mfma_f32_16x16x32_bf16 v[100:103], v[204:207], v[108:111], v[100:103]
	v_mfma_f32_16x16x32_bf16 v[104:107], v[220:223], v[108:111], v[104:107]
	v_mfma_f32_16x16x32_bf16 v[108:111], v[200:203], v[112:115], v[176:179]
	v_mfma_f32_16x16x32_bf16 v[112:115], v[216:219], v[112:115], v[180:183]
	v_mfma_f32_16x16x32_bf16 v[116:119], v[200:203], v[228:231], v[184:187]
	v_mfma_f32_16x16x32_bf16 v[120:123], v[216:219], v[228:231], v[120:123]
	v_mfma_f32_16x16x32_bf16 v[124:127], v[200:203], v[236:239], v[188:191]
	v_mfma_f32_16x16x32_bf16 v[128:131], v[216:219], v[236:239], v[128:131]
	v_mfma_f32_16x16x32_bf16 v[108:111], v[204:207], v[224:227], v[108:111]
	v_mfma_f32_16x16x32_bf16 v[112:115], v[220:223], v[224:227], v[112:115]
	v_mfma_f32_16x16x32_bf16 v[116:119], v[204:207], v[232:235], v[116:119]
	v_mfma_f32_16x16x32_bf16 v[120:123], v[220:223], v[232:235], v[120:123]
	v_mfma_f32_16x16x32_bf16 v[124:127], v[204:207], v[250:253], v[124:127]
	v_mfma_f32_16x16x32_bf16 v[128:131], v[220:223], v[250:253], v[128:131]
	s_setprio 0
	s_barrier
	s_andn2_b64 vcc, exec, s[54:55]
	s_cbranch_vccnz .LBB0_857
	s_add_u32 s88, s20, 0x200
	s_addc_u32 s89, s21, 0
	s_add_u32 s26, s26, 0x200
	s_addc_u32 s27, s27, 0
	s_mov_b32 s90, 4
	.p2align	6

.LBB0_878:
	s_add_u32 s16, s26, 0x100
	s_addc_u32 s17, s27, 0
	s_add_u32 s18, s20, 0x100
	s_addc_u32 s19, s21, 0
	s_and_b64 s[8:9], s[54:55], exec
	s_cselect_b32 s31, s43, s19
	s_cselect_b32 s30, s42, s18
	s_add_i32 s82, 0, 0x10000
	s_and_b64 s[8:9], s[54:55], exec
	s_cselect_b32 s19, s41, s17
	s_cselect_b32 s18, s40, s16
	s_add_i32 s84, 0, 0x14000
	v_add_u32_e32 v132, s82, v245
	v_add_u32_e32 v133, s84, v245
	ds_read_b128 v[4:7], v132
	ds_read_b128 v[8:11], v132 offset:1024
	ds_read_b128 v[12:15], v132 offset:2048
	ds_read_b128 v[16:19], v132 offset:3072
	ds_read_b128 v[20:23], v133
	ds_read_b128 v[24:27], v133 offset:1024
	ds_read_b128 v[28:31], v133 offset:2048
	ds_read_b128 v[32:35], v133 offset:3072
	s_add_u32 s8, s26, 0x80
	s_addc_u32 s9, s27, 0
	s_add_i32 s78, s7, 0x8000
	s_add_i32 s79, s7, 0xa000
	s_mov_b64 s[16:17], s[8:9]
	s_mov_b32 m0, s78
	s_add_u32 s8, s8, s46
	ds_read_b128 v[36:39], v246
	ds_read_b128 v[40:43], v246 offset:1024
	ds_read_b128 v[44:47], v246 offset:2048
	ds_read_b128 v[48:51], v246 offset:3072
	ds_read_b128 v[52:55], v246 offset:4096
	ds_read_b128 v[56:59], v246 offset:5120
	ds_read_b128 v[60:63], v246 offset:6144
	ds_read_b128 v[64:67], v246 offset:7168
	s_addc_u32 s9, s9, s47
	global_load_lds_dwordx4 v242, s[16:17]
	s_mov_b32 m0, s79
	s_add_i32 s80, s7, 0xc000
	global_load_lds_dwordx4 v2, s[16:17]
	s_mov_b32 m0, s80
	s_add_i32 s81, s7, 0xe000
	s_add_u32 s28, s30, 0x80
	global_load_lds_dwordx4 v242, s[8:9]
	s_mov_b32 m0, s81
	s_addc_u32 s29, s31, 0
	global_load_lds_dwordx4 v2, s[8:9]
	s_waitcnt vmcnt(8)
	s_waitcnt lgkmcnt(0)
	s_barrier
	s_setprio 1
	s_waitcnt lgkmcnt(0)
	v_mfma_f32_16x16x32_bf16 v[68:71], v[4:7], v[36:39], 0
	v_mfma_f32_16x16x32_bf16 v[72:75], v[12:15], v[36:39], 0
	v_mfma_f32_16x16x32_bf16 v[76:79], v[4:7], v[44:47], 0
	v_mfma_f32_16x16x32_bf16 v[80:83], v[12:15], v[44:47], 0
	v_mfma_f32_16x16x32_bf16 v[84:87], v[4:7], v[52:55], 0
	v_mfma_f32_16x16x32_bf16 v[88:91], v[12:15], v[52:55], 0
	v_mfma_f32_16x16x32_bf16 v[92:95], v[4:7], v[60:63], 0
	v_mfma_f32_16x16x32_bf16 v[96:99], v[12:15], v[60:63], 0
	v_mfma_f32_16x16x32_bf16 v[68:71], v[8:11], v[40:43], v[68:71]
	v_mfma_f32_16x16x32_bf16 v[72:75], v[16:19], v[40:43], v[72:75]
	v_mfma_f32_16x16x32_bf16 v[76:79], v[8:11], v[48:51], v[76:79]
	v_mfma_f32_16x16x32_bf16 v[80:83], v[16:19], v[48:51], v[80:83]
	v_mfma_f32_16x16x32_bf16 v[84:87], v[8:11], v[56:59], v[84:87]
	v_mfma_f32_16x16x32_bf16 v[88:91], v[16:19], v[56:59], v[88:91]
	v_mfma_f32_16x16x32_bf16 v[92:95], v[8:11], v[64:67], v[92:95]
	v_mfma_f32_16x16x32_bf16 v[96:99], v[16:19], v[64:67], v[96:99]
	s_setprio 0
	s_setprio 1
	v_mfma_f32_16x16x32_bf16 v[100:103], v[20:23], v[36:39], 0
	v_mfma_f32_16x16x32_bf16 v[36:39], v[28:31], v[36:39], 0
	v_mfma_f32_16x16x32_bf16 v[100:103], v[24:27], v[40:43], v[100:103]
	v_mfma_f32_16x16x32_bf16 v[40:43], v[32:35], v[40:43], v[36:39]
	v_mfma_f32_16x16x32_bf16 v[36:39], v[20:23], v[44:47], 0
	v_mfma_f32_16x16x32_bf16 v[104:107], v[24:27], v[48:51], v[36:39]
	v_mfma_f32_16x16x32_bf16 v[36:39], v[28:31], v[44:47], 0
	v_mfma_f32_16x16x32_bf16 v[48:51], v[32:35], v[48:51], v[36:39]
	v_mfma_f32_16x16x32_bf16 v[36:39], v[20:23], v[52:55], 0
	v_mfma_f32_16x16x32_bf16 v[108:111], v[24:27], v[56:59], v[36:39]
	v_mfma_f32_16x16x32_bf16 v[36:39], v[28:31], v[52:55], 0
	v_mfma_f32_16x16x32_bf16 v[56:59], v[32:35], v[56:59], v[36:39]
	v_mfma_f32_16x16x32_bf16 v[36:39], v[20:23], v[60:63], 0
	v_mfma_f32_16x16x32_bf16 v[112:115], v[24:27], v[64:67], v[36:39]
	v_mfma_f32_16x16x32_bf16 v[36:39], v[28:31], v[60:63], 0
	v_mfma_f32_16x16x32_bf16 v[64:67], v[32:35], v[64:67], v[36:39]
	s_setprio 0
	s_barrier
	s_add_i32 s82, s82, s6
	s_mov_b64 s[8:9], s[30:31]
	s_mov_b32 m0, s82
	s_add_i32 s83, s82, 0x2000
	s_nop 0
	ds_read_b128 v[36:39], v246 offset:16384
	ds_read_b128 v[44:47], v246 offset:17408
	ds_read_b128 v[52:55], v246 offset:18432
	ds_read_b128 v[60:63], v246 offset:19456
	ds_read_b128 v[116:119], v246 offset:20480
	ds_read_b128 v[120:123], v246 offset:21504
	ds_read_b128 v[124:127], v246 offset:22528
	ds_read_b128 v[128:131], v246 offset:23552
	s_nop 0
	global_load_lds_dwordx4 v248, s[8:9]
	s_mov_b32 m0, s83
	s_nop 0
	global_load_lds_dwordx4 v247, s[8:9]
	s_add_u32 s8, s30, s46
	s_addc_u32 s9, s31, s47
	s_add_i32 s30, s84, s6
	s_mov_b32 m0, s30
	s_add_i32 s31, s30, 0x2000
	s_nop 0
	global_load_lds_dwordx4 v248, s[8:9]
	s_mov_b32 m0, s31
	s_nop 0
	global_load_lds_dwordx4 v247, s[8:9]
	s_waitcnt vmcnt(6)
	s_waitcnt lgkmcnt(0)
	s_barrier
	s_setprio 1
	s_waitcnt lgkmcnt(0)
	v_mfma_f32_16x16x32_bf16 v[134:137], v[4:7], v[36:39], 0
	v_mfma_f32_16x16x32_bf16 v[144:147], v[4:7], v[52:55], 0
	v_mfma_f32_16x16x32_bf16 v[152:155], v[4:7], v[116:119], 0
	v_mfma_f32_16x16x32_bf16 v[4:7], v[4:7], v[124:127], 0
	v_mfma_f32_16x16x32_bf16 v[140:143], v[12:15], v[36:39], 0
	v_mfma_f32_16x16x32_bf16 v[148:151], v[12:15], v[52:55], 0
	v_mfma_f32_16x16x32_bf16 v[156:159], v[12:15], v[116:119], 0
	v_mfma_f32_16x16x32_bf16 v[160:163], v[8:11], v[128:131], v[4:7]
	v_mfma_f32_16x16x32_bf16 v[4:7], v[12:15], v[124:127], 0
	v_mfma_f32_16x16x32_bf16 v[136:139], v[8:11], v[44:47], v[134:137]
	v_mfma_f32_16x16x32_bf16 v[140:143], v[16:19], v[44:47], v[140:143]
	v_mfma_f32_16x16x32_bf16 v[144:147], v[8:11], v[60:63], v[144:147]
	v_mfma_f32_16x16x32_bf16 v[148:151], v[16:19], v[60:63], v[148:151]
	v_mfma_f32_16x16x32_bf16 v[152:155], v[8:11], v[120:123], v[152:155]
	v_mfma_f32_16x16x32_bf16 v[156:159], v[16:19], v[120:123], v[156:159]
	v_mfma_f32_16x16x32_bf16 v[164:167], v[16:19], v[128:131], v[4:7]
	s_setprio 0
	s_setprio 1
	v_mfma_f32_16x16x32_bf16 v[4:7], v[20:23], v[36:39], 0
	v_mfma_f32_16x16x32_bf16 v[168:171], v[24:27], v[44:47], v[4:7]
	v_mfma_f32_16x16x32_bf16 v[4:7], v[28:31], v[36:39], 0
	v_mfma_f32_16x16x32_bf16 v[172:175], v[32:35], v[44:47], v[4:7]
	v_mfma_f32_16x16x32_bf16 v[4:7], v[20:23], v[52:55], 0
	v_mfma_f32_16x16x32_bf16 v[176:179], v[24:27], v[60:63], v[4:7]
	v_mfma_f32_16x16x32_bf16 v[4:7], v[28:31], v[52:55], 0
	v_mfma_f32_16x16x32_bf16 v[180:183], v[32:35], v[60:63], v[4:7]
	v_mfma_f32_16x16x32_bf16 v[4:7], v[20:23], v[116:119], 0
	v_mfma_f32_16x16x32_bf16 v[184:187], v[24:27], v[120:123], v[4:7]
	v_mfma_f32_16x16x32_bf16 v[4:7], v[28:31], v[116:119], 0
	v_mfma_f32_16x16x32_bf16 v[120:123], v[32:35], v[120:123], v[4:7]
	v_mfma_f32_16x16x32_bf16 v[4:7], v[20:23], v[124:127], 0
	v_mfma_f32_16x16x32_bf16 v[188:191], v[24:27], v[128:131], v[4:7]
	v_mfma_f32_16x16x32_bf16 v[4:7], v[28:31], v[124:127], 0
	v_mfma_f32_16x16x32_bf16 v[128:131], v[32:35], v[128:131], v[4:7]
	s_setprio 0
	s_barrier
	s_add_i32 s84, 0, 0x18000
	s_add_i32 s16, 0, 0x1c000
	v_add_u32_e32 v134, s84, v245
	v_add_u32_e32 v135, s16, v245
	ds_read_b128 v[116:119], v134
	ds_read_b128 v[124:127], v134 offset:1024
	ds_read_b128 v[192:195], v134 offset:2048
	ds_read_b128 v[196:199], v134 offset:3072
	ds_read_b128 v[200:203], v135
	ds_read_b128 v[204:207], v135 offset:1024
	ds_read_b128 v[216:219], v135 offset:2048
	ds_read_b128 v[220:223], v135 offset:3072
	s_mov_b32 m0, s7
	s_mov_b64 s[8:9], s[18:19]
	ds_read_b128 v[44:47], v246 offset:32768
	ds_read_b128 v[52:55], v246 offset:33792
	ds_read_b128 v[60:63], v246 offset:34816
	ds_read_b128 v[224:227], v246 offset:35840
	ds_read_b128 v[228:231], v246 offset:36864
	ds_read_b128 v[232:235], v246 offset:37888
	ds_read_b128 v[236:239], v246 offset:38912
	ds_read_b128 v[250:253], v246 offset:39936
	s_nop 0
	global_load_lds_dwordx4 v242, s[8:9]
	s_mov_b32 m0, s58
	s_nop 0
	global_load_lds_dwordx4 v2, s[8:9]
	s_add_u32 s8, s18, s46
	s_addc_u32 s9, s19, s47
	s_mov_b32 m0, s59
	s_nop 0
	global_load_lds_dwordx4 v242, s[8:9]
	s_mov_b32 m0, s69
	s_nop 0
	global_load_lds_dwordx4 v2, s[8:9]
	s_waitcnt vmcnt(8)
	s_waitcnt lgkmcnt(0)
	s_barrier
	s_setprio 1
	s_waitcnt lgkmcnt(0)
	v_mfma_f32_16x16x32_bf16 v[4:7], v[116:119], v[44:47], v[68:71]
	v_mfma_f32_16x16x32_bf16 v[4:7], v[124:127], v[52:55], v[4:7]
	v_mfma_f32_16x16x32_bf16 v[8:11], v[192:195], v[44:47], v[72:75]
	v_mfma_f32_16x16x32_bf16 v[8:11], v[196:199], v[52:55], v[8:11]
	v_mfma_f32_16x16x32_bf16 v[12:15], v[116:119], v[60:63], v[76:79]
	v_mfma_f32_16x16x32_bf16 v[12:15], v[124:127], v[224:227], v[12:15]
	v_mfma_f32_16x16x32_bf16 v[16:19], v[192:195], v[60:63], v[80:83]
	v_mfma_f32_16x16x32_bf16 v[16:19], v[196:199], v[224:227], v[16:19]
	v_mfma_f32_16x16x32_bf16 v[20:23], v[116:119], v[228:231], v[84:87]
	v_mfma_f32_16x16x32_bf16 v[20:23], v[124:127], v[232:235], v[20:23]
	v_mfma_f32_16x16x32_bf16 v[24:27], v[192:195], v[228:231], v[88:91]
	v_mfma_f32_16x16x32_bf16 v[24:27], v[196:199], v[232:235], v[24:27]
	v_mfma_f32_16x16x32_bf16 v[28:31], v[116:119], v[236:239], v[92:95]
	v_mfma_f32_16x16x32_bf16 v[28:31], v[124:127], v[250:253], v[28:31]
	v_mfma_f32_16x16x32_bf16 v[32:35], v[192:195], v[236:239], v[96:99]
	v_mfma_f32_16x16x32_bf16 v[32:35], v[196:199], v[250:253], v[32:35]
	s_setprio 0
	s_setprio 1
	v_mfma_f32_16x16x32_bf16 v[36:39], v[200:203], v[44:47], v[100:103]
	v_mfma_f32_16x16x32_bf16 v[40:43], v[216:219], v[44:47], v[40:43]
	v_mfma_f32_16x16x32_bf16 v[36:39], v[204:207], v[52:55], v[36:39]
	v_mfma_f32_16x16x32_bf16 v[40:43], v[220:223], v[52:55], v[40:43]
	v_mfma_f32_16x16x32_bf16 v[44:47], v[200:203], v[60:63], v[104:107]
	v_mfma_f32_16x16x32_bf16 v[48:51], v[216:219], v[60:63], v[48:51]
	v_mfma_f32_16x16x32_bf16 v[52:55], v[200:203], v[228:231], v[108:111]
	v_mfma_f32_16x16x32_bf16 v[56:59], v[216:219], v[228:231], v[56:59]
	v_mfma_f32_16x16x32_bf16 v[60:63], v[200:203], v[236:239], v[112:115]
	v_mfma_f32_16x16x32_bf16 v[64:67], v[216:219], v[236:239], v[64:67]
	v_mfma_f32_16x16x32_bf16 v[44:47], v[204:207], v[224:227], v[44:47]
	v_mfma_f32_16x16x32_bf16 v[48:51], v[220:223], v[224:227], v[48:51]
	v_mfma_f32_16x16x32_bf16 v[52:55], v[204:207], v[232:235], v[52:55]
	v_mfma_f32_16x16x32_bf16 v[56:59], v[220:223], v[232:235], v[56:59]
	v_mfma_f32_16x16x32_bf16 v[60:63], v[204:207], v[250:253], v[60:63]
	v_mfma_f32_16x16x32_bf16 v[64:67], v[220:223], v[250:253], v[64:67]
	s_setprio 0
	s_barrier
	s_add_i32 s84, s84, s6
	s_mov_b64 s[8:9], s[28:29]
	s_mov_b32 m0, s84
	s_add_i32 s85, s84, 0x2000
	ds_read_b128 v[104:107], v246 offset:49152
	ds_read_b128 v[108:111], v246 offset:50176
	ds_read_b128 v[112:115], v246 offset:51200
	ds_read_b128 v[224:227], v246 offset:52224
	ds_read_b128 v[228:231], v246 offset:53248
	ds_read_b128 v[232:235], v246 offset:54272
	ds_read_b128 v[236:239], v246 offset:55296
	ds_read_b128 v[250:253], v246 offset:56320
	s_nop 0
	global_load_lds_dwordx4 v248, s[8:9]
	s_mov_b32 m0, s85
	s_nop 0
	global_load_lds_dwordx4 v247, s[8:9]
	s_add_u32 s8, s28, s46
	s_addc_u32 s9, s29, s47
	s_add_i32 s28, s16, s6
	s_mov_b32 m0, s28
	s_add_i32 s29, s28, 0x2000
	s_nop 0
	global_load_lds_dwordx4 v248, s[8:9]
	s_mov_b32 m0, s29
	s_nop 0
	global_load_lds_dwordx4 v247, s[8:9]
	s_waitcnt vmcnt(6)
	s_waitcnt lgkmcnt(0)
	s_barrier
	s_setprio 1
	s_waitcnt lgkmcnt(0)
	v_mfma_f32_16x16x32_bf16 v[68:71], v[116:119], v[104:107], v[136:139]
	v_mfma_f32_16x16x32_bf16 v[68:71], v[124:127], v[108:111], v[68:71]
	v_mfma_f32_16x16x32_bf16 v[72:75], v[192:195], v[104:107], v[140:143]
	v_mfma_f32_16x16x32_bf16 v[72:75], v[196:199], v[108:111], v[72:75]
	v_mfma_f32_16x16x32_bf16 v[76:79], v[116:119], v[112:115], v[144:147]
	v_mfma_f32_16x16x32_bf16 v[76:79], v[124:127], v[224:227], v[76:79]
	v_mfma_f32_16x16x32_bf16 v[80:83], v[192:195], v[112:115], v[148:151]
	v_mfma_f32_16x16x32_bf16 v[80:83], v[196:199], v[224:227], v[80:83]
	v_mfma_f32_16x16x32_bf16 v[84:87], v[116:119], v[228:231], v[152:155]
	v_mfma_f32_16x16x32_bf16 v[84:87], v[124:127], v[232:235], v[84:87]
	v_mfma_f32_16x16x32_bf16 v[88:91], v[192:195], v[228:231], v[156:159]
	v_mfma_f32_16x16x32_bf16 v[88:91], v[196:199], v[232:235], v[88:91]
	v_mfma_f32_16x16x32_bf16 v[92:95], v[116:119], v[236:239], v[160:163]
	v_mfma_f32_16x16x32_bf16 v[92:95], v[124:127], v[250:253], v[92:95]
	v_mfma_f32_16x16x32_bf16 v[96:99], v[192:195], v[236:239], v[164:167]
	v_mfma_f32_16x16x32_bf16 v[96:99], v[196:199], v[250:253], v[96:99]
	s_setprio 0
	s_setprio 1
	v_mfma_f32_16x16x32_bf16 v[100:103], v[200:203], v[104:107], v[168:171]
	v_mfma_f32_16x16x32_bf16 v[104:107], v[216:219], v[104:107], v[172:175]
	v_mfma_f32_16x16x32_bf16 v[100:103], v[204:207], v[108:111], v[100:103]
	v_mfma_f32_16x16x32_bf16 v[104:107], v[220:223], v[108:111], v[104:107]
	v_mfma_f32_16x16x32_bf16 v[108:111], v[200:203], v[112:115], v[176:179]
	v_mfma_f32_16x16x32_bf16 v[112:115], v[216:219], v[112:115], v[180:183]
	v_mfma_f32_16x16x32_bf16 v[116:119], v[200:203], v[228:231], v[184:187]
	v_mfma_f32_16x16x32_bf16 v[120:123], v[216:219], v[228:231], v[120:123]
	v_mfma_f32_16x16x32_bf16 v[124:127], v[200:203], v[236:239], v[188:191]
	v_mfma_f32_16x16x32_bf16 v[128:131], v[216:219], v[236:239], v[128:131]
	v_mfma_f32_16x16x32_bf16 v[108:111], v[204:207], v[224:227], v[108:111]
	v_mfma_f32_16x16x32_bf16 v[112:115], v[220:223], v[224:227], v[112:115]
	v_mfma_f32_16x16x32_bf16 v[116:119], v[204:207], v[232:235], v[116:119]
	v_mfma_f32_16x16x32_bf16 v[120:123], v[220:223], v[232:235], v[120:123]
	v_mfma_f32_16x16x32_bf16 v[124:127], v[204:207], v[250:253], v[124:127]
	v_mfma_f32_16x16x32_bf16 v[128:131], v[220:223], v[250:253], v[128:131]
	s_setprio 0
	s_barrier
	s_andn2_b64 vcc, exec, s[56:57]
	s_cbranch_vccnz .LBB0_881
	s_add_u32 s86, s20, 0x200
	s_addc_u32 s87, s21, 0
	s_add_u32 s26, s26, 0x200
	s_addc_u32 s27, s27, 0
	s_mov_b32 s88, 4
	.p2align	6

.LBB0_1019:
	s_add_u32 s18, s72, 0x100
	s_addc_u32 s19, s73, 0
	s_add_u32 s16, s66, 0x100
	s_addc_u32 s17, s67, 0
	s_and_b64 s[8:9], s[30:31], exec
	s_cselect_b32 s17, s43, s17
	s_cselect_b32 s16, s42, s16
	s_add_i32 s89, 0, 0x10000
	s_and_b64 s[8:9], s[30:31], exec
	s_cselect_b32 s69, s65, s19
	s_cselect_b32 s68, s64, s18
	s_add_i32 s91, 0, 0x14000
	v_add_u32_e32 v132, s89, v140
	v_add_u32_e32 v133, s91, v140
	ds_read_b128 v[4:7], v132
	ds_read_b128 v[8:11], v132 offset:1024
	ds_read_b128 v[12:15], v132 offset:2048
	ds_read_b128 v[16:19], v132 offset:3072
	ds_read_b128 v[20:23], v133
	ds_read_b128 v[24:27], v133 offset:1024
	ds_read_b128 v[28:31], v133 offset:2048
	ds_read_b128 v[32:35], v133 offset:3072
	s_add_u32 s8, s72, 0x80
	s_addc_u32 s9, s73, 0
	s_add_i32 s85, s78, 0x8000
	s_add_i32 s86, s78, 0xa000
	s_mov_b64 s[18:19], s[8:9]
	s_mov_b32 m0, s85
	s_add_u32 s8, s8, s20
	ds_read_b128 v[36:39], v141 offset:8192
	ds_read_b128 v[40:43], v141 offset:9216
	ds_read_b128 v[44:47], v141 offset:10240
	ds_read_b128 v[48:51], v141 offset:11264
	ds_read_b128 v[52:55], v141 offset:12288
	ds_read_b128 v[56:59], v141 offset:13312
	ds_read_b128 v[60:63], v141 offset:14336
	ds_read_b128 v[64:67], v141 offset:15360
	s_addc_u32 s9, s9, s21
	global_load_lds_dwordx4 v137, s[18:19]
	s_mov_b32 m0, s86
	s_add_i32 s87, s78, 0xc000
	global_load_lds_dwordx4 v136, s[18:19]
	s_mov_b32 m0, s87
	s_add_i32 s88, s78, 0xe000
	s_add_u32 s18, s16, 0x80
	global_load_lds_dwordx4 v137, s[8:9]
	s_mov_b32 m0, s88
	s_addc_u32 s19, s17, 0
	global_load_lds_dwordx4 v136, s[8:9]
	s_waitcnt vmcnt(8)
	s_waitcnt lgkmcnt(0)
	s_barrier
	s_setprio 1
	s_waitcnt lgkmcnt(0)
	v_mfma_f32_16x16x32_bf16 v[68:71], v[4:7], v[36:39], 0
	v_mfma_f32_16x16x32_bf16 v[72:75], v[12:15], v[36:39], 0
	v_mfma_f32_16x16x32_bf16 v[76:79], v[4:7], v[44:47], 0
	v_mfma_f32_16x16x32_bf16 v[80:83], v[12:15], v[44:47], 0
	v_mfma_f32_16x16x32_bf16 v[84:87], v[4:7], v[52:55], 0
	v_mfma_f32_16x16x32_bf16 v[88:91], v[12:15], v[52:55], 0
	v_mfma_f32_16x16x32_bf16 v[92:95], v[4:7], v[60:63], 0
	v_mfma_f32_16x16x32_bf16 v[96:99], v[12:15], v[60:63], 0
	v_mfma_f32_16x16x32_bf16 v[68:71], v[8:11], v[40:43], v[68:71]
	v_mfma_f32_16x16x32_bf16 v[72:75], v[16:19], v[40:43], v[72:75]
	v_mfma_f32_16x16x32_bf16 v[76:79], v[8:11], v[48:51], v[76:79]
	v_mfma_f32_16x16x32_bf16 v[80:83], v[16:19], v[48:51], v[80:83]
	v_mfma_f32_16x16x32_bf16 v[84:87], v[8:11], v[56:59], v[84:87]
	v_mfma_f32_16x16x32_bf16 v[88:91], v[16:19], v[56:59], v[88:91]
	v_mfma_f32_16x16x32_bf16 v[92:95], v[8:11], v[64:67], v[92:95]
	v_mfma_f32_16x16x32_bf16 v[96:99], v[16:19], v[64:67], v[96:99]
	s_setprio 0
	s_setprio 1
	v_mfma_f32_16x16x32_bf16 v[100:103], v[20:23], v[36:39], 0
	v_mfma_f32_16x16x32_bf16 v[36:39], v[28:31], v[36:39], 0
	v_mfma_f32_16x16x32_bf16 v[100:103], v[24:27], v[40:43], v[100:103]
	v_mfma_f32_16x16x32_bf16 v[40:43], v[32:35], v[40:43], v[36:39]
	v_mfma_f32_16x16x32_bf16 v[36:39], v[20:23], v[44:47], 0
	v_mfma_f32_16x16x32_bf16 v[104:107], v[24:27], v[48:51], v[36:39]
	v_mfma_f32_16x16x32_bf16 v[36:39], v[28:31], v[44:47], 0
	v_mfma_f32_16x16x32_bf16 v[48:51], v[32:35], v[48:51], v[36:39]
	v_mfma_f32_16x16x32_bf16 v[36:39], v[20:23], v[52:55], 0
	v_mfma_f32_16x16x32_bf16 v[108:111], v[24:27], v[56:59], v[36:39]
	v_mfma_f32_16x16x32_bf16 v[36:39], v[28:31], v[52:55], 0
	v_mfma_f32_16x16x32_bf16 v[56:59], v[32:35], v[56:59], v[36:39]
	v_mfma_f32_16x16x32_bf16 v[36:39], v[20:23], v[60:63], 0
	v_mfma_f32_16x16x32_bf16 v[112:115], v[24:27], v[64:67], v[36:39]
	v_mfma_f32_16x16x32_bf16 v[36:39], v[28:31], v[60:63], 0
	v_mfma_f32_16x16x32_bf16 v[64:67], v[32:35], v[64:67], v[36:39]
	s_setprio 0
	s_barrier
	s_add_i32 s89, s89, s77
	s_mov_b64 s[8:9], s[16:17]
	s_mov_b32 m0, s89
	s_add_i32 s90, s89, 0x2000
	s_nop 0
	ds_read_b128 v[36:39], v141 offset:24576
	ds_read_b128 v[44:47], v141 offset:25600
	ds_read_b128 v[52:55], v141 offset:26624
	ds_read_b128 v[60:63], v141 offset:27648
	ds_read_b128 v[116:119], v141 offset:28672
	ds_read_b128 v[120:123], v141 offset:29696
	ds_read_b128 v[124:127], v141 offset:30720
	ds_read_b128 v[128:131], v141 offset:31744
	s_nop 0
	global_load_lds_dwordx4 v143, s[8:9]
	s_mov_b32 m0, s90
	s_nop 0
	global_load_lds_dwordx4 v142, s[8:9]
	s_add_u32 s8, s16, s20
	s_addc_u32 s9, s17, s21
	s_add_i32 s91, s91, s77
	s_mov_b32 m0, s91
	s_add_i32 s92, s91, 0x2000
	s_nop 0
	global_load_lds_dwordx4 v143, s[8:9]
	s_mov_b32 m0, s92
	s_nop 0
	global_load_lds_dwordx4 v142, s[8:9]
	s_waitcnt vmcnt(6)
	s_waitcnt lgkmcnt(0)
	s_barrier
	s_setprio 1
	s_waitcnt lgkmcnt(0)
	v_mfma_f32_16x16x32_bf16 v[144:147], v[4:7], v[36:39], 0
	v_mfma_f32_16x16x32_bf16 v[152:155], v[4:7], v[52:55], 0
	v_mfma_f32_16x16x32_bf16 v[160:163], v[4:7], v[116:119], 0
	v_mfma_f32_16x16x32_bf16 v[4:7], v[4:7], v[124:127], 0
	v_mfma_f32_16x16x32_bf16 v[148:151], v[12:15], v[36:39], 0
	v_mfma_f32_16x16x32_bf16 v[156:159], v[12:15], v[52:55], 0
	v_mfma_f32_16x16x32_bf16 v[164:167], v[12:15], v[116:119], 0
	v_mfma_f32_16x16x32_bf16 v[168:171], v[8:11], v[128:131], v[4:7]
	v_mfma_f32_16x16x32_bf16 v[4:7], v[12:15], v[124:127], 0
	v_mfma_f32_16x16x32_bf16 v[144:147], v[8:11], v[44:47], v[144:147]
	v_mfma_f32_16x16x32_bf16 v[148:151], v[16:19], v[44:47], v[148:151]
	v_mfma_f32_16x16x32_bf16 v[152:155], v[8:11], v[60:63], v[152:155]
	v_mfma_f32_16x16x32_bf16 v[156:159], v[16:19], v[60:63], v[156:159]
	v_mfma_f32_16x16x32_bf16 v[160:163], v[8:11], v[120:123], v[160:163]
	v_mfma_f32_16x16x32_bf16 v[164:167], v[16:19], v[120:123], v[164:167]
	v_mfma_f32_16x16x32_bf16 v[172:175], v[16:19], v[128:131], v[4:7]
	s_setprio 0
	s_setprio 1
	v_mfma_f32_16x16x32_bf16 v[4:7], v[20:23], v[36:39], 0
	v_mfma_f32_16x16x32_bf16 v[176:179], v[24:27], v[44:47], v[4:7]
	v_mfma_f32_16x16x32_bf16 v[4:7], v[28:31], v[36:39], 0
	v_mfma_f32_16x16x32_bf16 v[180:183], v[32:35], v[44:47], v[4:7]
	v_mfma_f32_16x16x32_bf16 v[4:7], v[20:23], v[52:55], 0
	v_mfma_f32_16x16x32_bf16 v[184:187], v[24:27], v[60:63], v[4:7]
	v_mfma_f32_16x16x32_bf16 v[4:7], v[28:31], v[52:55], 0
	v_mfma_f32_16x16x32_bf16 v[188:191], v[32:35], v[60:63], v[4:7]
	v_mfma_f32_16x16x32_bf16 v[4:7], v[20:23], v[116:119], 0
	v_mfma_f32_16x16x32_bf16 v[192:195], v[24:27], v[120:123], v[4:7]
	v_mfma_f32_16x16x32_bf16 v[4:7], v[28:31], v[116:119], 0
	v_mfma_f32_16x16x32_bf16 v[120:123], v[32:35], v[120:123], v[4:7]
	v_mfma_f32_16x16x32_bf16 v[4:7], v[20:23], v[124:127], 0
	v_mfma_f32_16x16x32_bf16 v[196:199], v[24:27], v[128:131], v[4:7]
	v_mfma_f32_16x16x32_bf16 v[4:7], v[28:31], v[124:127], 0
	v_mfma_f32_16x16x32_bf16 v[128:131], v[32:35], v[128:131], v[4:7]
	s_setprio 0
	s_barrier
	s_add_i32 s16, 0, 0x18000
	s_add_i32 s93, 0, 0x1c000
	v_add_u32_e32 v134, s16, v140
	v_add_u32_e32 v135, s93, v140
	ds_read_b128 v[116:119], v134
	ds_read_b128 v[124:127], v134 offset:1024
	ds_read_b128 v[200:203], v134 offset:2048
	ds_read_b128 v[204:207], v134 offset:3072
	ds_read_b128 v[216:219], v135
	ds_read_b128 v[220:223], v135 offset:1024
	ds_read_b128 v[224:227], v135 offset:2048
	ds_read_b128 v[228:231], v135 offset:3072
	s_mov_b32 m0, s78
	s_mov_b64 s[8:9], s[68:69]
	ds_read_b128 v[44:47], v141 offset:40960
	ds_read_b128 v[52:55], v141 offset:41984
	ds_read_b128 v[60:63], v141 offset:43008
	ds_read_b128 v[232:235], v141 offset:44032
	ds_read_b128 v[236:239], v141 offset:45056
	ds_read_b128 v[242:245], v141 offset:46080
	ds_read_b128 v[246:249], v141 offset:47104
	ds_read_b128 v[250:253], v141 offset:48128
	s_nop 0
	global_load_lds_dwordx4 v137, s[8:9]
	s_mov_b32 m0, s79
	s_nop 0
	global_load_lds_dwordx4 v136, s[8:9]
	s_add_u32 s8, s68, s20
	s_addc_u32 s9, s69, s21
	s_mov_b32 m0, s80
	s_nop 0
	global_load_lds_dwordx4 v137, s[8:9]
	s_mov_b32 m0, s81
	s_nop 0
	global_load_lds_dwordx4 v136, s[8:9]
	s_waitcnt vmcnt(8)
	s_waitcnt lgkmcnt(0)
	s_barrier
	s_setprio 1
	s_waitcnt lgkmcnt(0)
	v_mfma_f32_16x16x32_bf16 v[4:7], v[116:119], v[44:47], v[68:71]
	v_mfma_f32_16x16x32_bf16 v[4:7], v[124:127], v[52:55], v[4:7]
	v_mfma_f32_16x16x32_bf16 v[8:11], v[200:203], v[44:47], v[72:75]
	v_mfma_f32_16x16x32_bf16 v[8:11], v[204:207], v[52:55], v[8:11]
	v_mfma_f32_16x16x32_bf16 v[12:15], v[116:119], v[60:63], v[76:79]
	v_mfma_f32_16x16x32_bf16 v[12:15], v[124:127], v[232:235], v[12:15]
	v_mfma_f32_16x16x32_bf16 v[16:19], v[200:203], v[60:63], v[80:83]
	v_mfma_f32_16x16x32_bf16 v[16:19], v[204:207], v[232:235], v[16:19]
	v_mfma_f32_16x16x32_bf16 v[20:23], v[116:119], v[236:239], v[84:87]
	v_mfma_f32_16x16x32_bf16 v[20:23], v[124:127], v[242:245], v[20:23]
	v_mfma_f32_16x16x32_bf16 v[24:27], v[200:203], v[236:239], v[88:91]
	v_mfma_f32_16x16x32_bf16 v[24:27], v[204:207], v[242:245], v[24:27]
	v_mfma_f32_16x16x32_bf16 v[28:31], v[116:119], v[246:249], v[92:95]
	v_mfma_f32_16x16x32_bf16 v[28:31], v[124:127], v[250:253], v[28:31]
	v_mfma_f32_16x16x32_bf16 v[32:35], v[200:203], v[246:249], v[96:99]
	v_mfma_f32_16x16x32_bf16 v[32:35], v[204:207], v[250:253], v[32:35]
	s_setprio 0
	s_setprio 1
	v_mfma_f32_16x16x32_bf16 v[36:39], v[216:219], v[44:47], v[100:103]
	v_mfma_f32_16x16x32_bf16 v[40:43], v[224:227], v[44:47], v[40:43]
	v_mfma_f32_16x16x32_bf16 v[36:39], v[220:223], v[52:55], v[36:39]
	v_mfma_f32_16x16x32_bf16 v[40:43], v[228:231], v[52:55], v[40:43]
	v_mfma_f32_16x16x32_bf16 v[44:47], v[216:219], v[60:63], v[104:107]
	v_mfma_f32_16x16x32_bf16 v[48:51], v[224:227], v[60:63], v[48:51]
	v_mfma_f32_16x16x32_bf16 v[52:55], v[216:219], v[236:239], v[108:111]
	v_mfma_f32_16x16x32_bf16 v[56:59], v[224:227], v[236:239], v[56:59]
	v_mfma_f32_16x16x32_bf16 v[60:63], v[216:219], v[246:249], v[112:115]
	v_mfma_f32_16x16x32_bf16 v[64:67], v[224:227], v[246:249], v[64:67]
	v_mfma_f32_16x16x32_bf16 v[44:47], v[220:223], v[232:235], v[44:47]
	v_mfma_f32_16x16x32_bf16 v[48:51], v[228:231], v[232:235], v[48:51]
	v_mfma_f32_16x16x32_bf16 v[52:55], v[220:223], v[242:245], v[52:55]
	v_mfma_f32_16x16x32_bf16 v[56:59], v[228:231], v[242:245], v[56:59]
	v_mfma_f32_16x16x32_bf16 v[60:63], v[220:223], v[250:253], v[60:63]
	v_mfma_f32_16x16x32_bf16 v[64:67], v[228:231], v[250:253], v[64:67]
	s_setprio 0
	s_barrier
	s_add_i32 s68, s16, s77
	s_mov_b64 s[8:9], s[18:19]
	s_mov_b32 m0, s68
	s_add_i32 s69, s68, 0x2000
	ds_read_b128 v[104:107], v141 offset:57344
	ds_read_b128 v[108:111], v141 offset:58368
	ds_read_b128 v[112:115], v141 offset:59392
	ds_read_b128 v[232:235], v141 offset:60416
	ds_read_b128 v[236:239], v141 offset:61440
	ds_read_b128 v[242:245], v141 offset:62464
	ds_read_b128 v[246:249], v141 offset:63488
	ds_read_b128 v[250:253], v141 offset:64512
	s_nop 0
	global_load_lds_dwordx4 v143, s[8:9]
	s_mov_b32 m0, s69
	s_nop 0
	global_load_lds_dwordx4 v142, s[8:9]
	s_add_u32 s8, s18, s20
	s_addc_u32 s9, s19, s21
	s_add_i32 s93, s93, s77
	s_mov_b32 m0, s93
	s_add_i32 s94, s93, 0x2000
	s_nop 0
	global_load_lds_dwordx4 v143, s[8:9]
	s_mov_b32 m0, s94
	s_nop 0
	global_load_lds_dwordx4 v142, s[8:9]
	s_waitcnt vmcnt(6)
	s_waitcnt lgkmcnt(0)
	s_barrier
	s_setprio 1
	s_waitcnt lgkmcnt(0)
	v_mfma_f32_16x16x32_bf16 v[68:71], v[116:119], v[104:107], v[144:147]
	v_mfma_f32_16x16x32_bf16 v[68:71], v[124:127], v[108:111], v[68:71]
	v_mfma_f32_16x16x32_bf16 v[72:75], v[200:203], v[104:107], v[148:151]
	v_mfma_f32_16x16x32_bf16 v[72:75], v[204:207], v[108:111], v[72:75]
	v_mfma_f32_16x16x32_bf16 v[76:79], v[116:119], v[112:115], v[152:155]
	v_mfma_f32_16x16x32_bf16 v[76:79], v[124:127], v[232:235], v[76:79]
	v_mfma_f32_16x16x32_bf16 v[80:83], v[200:203], v[112:115], v[156:159]
	v_mfma_f32_16x16x32_bf16 v[80:83], v[204:207], v[232:235], v[80:83]
	v_mfma_f32_16x16x32_bf16 v[84:87], v[116:119], v[236:239], v[160:163]
	v_mfma_f32_16x16x32_bf16 v[84:87], v[124:127], v[242:245], v[84:87]
	v_mfma_f32_16x16x32_bf16 v[88:91], v[200:203], v[236:239], v[164:167]
	v_mfma_f32_16x16x32_bf16 v[88:91], v[204:207], v[242:245], v[88:91]
	v_mfma_f32_16x16x32_bf16 v[92:95], v[116:119], v[246:249], v[168:171]
	v_mfma_f32_16x16x32_bf16 v[92:95], v[124:127], v[250:253], v[92:95]
	v_mfma_f32_16x16x32_bf16 v[96:99], v[200:203], v[246:249], v[172:175]
	v_mfma_f32_16x16x32_bf16 v[96:99], v[204:207], v[250:253], v[96:99]
	s_setprio 0
	s_setprio 1
	v_mfma_f32_16x16x32_bf16 v[100:103], v[216:219], v[104:107], v[176:179]
	v_mfma_f32_16x16x32_bf16 v[104:107], v[224:227], v[104:107], v[180:183]
	v_mfma_f32_16x16x32_bf16 v[100:103], v[220:223], v[108:111], v[100:103]
	v_mfma_f32_16x16x32_bf16 v[104:107], v[228:231], v[108:111], v[104:107]
	v_mfma_f32_16x16x32_bf16 v[108:111], v[216:219], v[112:115], v[184:187]
	v_mfma_f32_16x16x32_bf16 v[112:115], v[224:227], v[112:115], v[188:191]
	v_mfma_f32_16x16x32_bf16 v[116:119], v[216:219], v[236:239], v[192:195]
	v_mfma_f32_16x16x32_bf16 v[120:123], v[224:227], v[236:239], v[120:123]
	v_mfma_f32_16x16x32_bf16 v[124:127], v[216:219], v[246:249], v[196:199]
	v_mfma_f32_16x16x32_bf16 v[128:131], v[224:227], v[246:249], v[128:131]
	v_mfma_f32_16x16x32_bf16 v[108:111], v[220:223], v[232:235], v[108:111]
	v_mfma_f32_16x16x32_bf16 v[112:115], v[228:231], v[232:235], v[112:115]
	v_mfma_f32_16x16x32_bf16 v[116:119], v[220:223], v[242:245], v[116:119]
	v_mfma_f32_16x16x32_bf16 v[120:123], v[228:231], v[242:245], v[120:123]
	v_mfma_f32_16x16x32_bf16 v[124:127], v[220:223], v[250:253], v[124:127]
	v_mfma_f32_16x16x32_bf16 v[128:131], v[228:231], v[250:253], v[128:131]
	s_setprio 0
	s_barrier
	s_andn2_b64 vcc, exec, s[60:61]
	s_cbranch_vccnz .LBB0_1023
	s_add_u32 s95, s66, 0x200
	s_addc_u32 s96, s67, 0
	s_add_u32 s72, s72, 0x200
	s_addc_u32 s73, s73, 0
	s_mov_b32 s97, 4
	.p2align	6

.LBB0_1040:
	s_add_u32 s18, s66, 0x100
	s_addc_u32 s19, s67, 0
	s_add_u32 s16, s64, 0x100
	s_addc_u32 s17, s65, 0
	s_and_b64 s[8:9], s[30:31], exec
	s_cselect_b32 s17, s43, s17
	s_cselect_b32 s16, s42, s16
	s_add_i32 s87, 0, 0x10000
	s_and_b64 s[8:9], s[30:31], exec
	s_cselect_b32 s69, s41, s19
	s_cselect_b32 s68, s40, s18
	s_add_i32 s89, 0, 0x14000
	v_add_u32_e32 v132, s87, v140
	v_add_u32_e32 v133, s89, v140
	ds_read_b128 v[4:7], v132
	ds_read_b128 v[8:11], v132 offset:1024
	ds_read_b128 v[12:15], v132 offset:2048
	ds_read_b128 v[16:19], v132 offset:3072
	ds_read_b128 v[20:23], v133
	ds_read_b128 v[24:27], v133 offset:1024
	ds_read_b128 v[28:31], v133 offset:2048
	ds_read_b128 v[32:35], v133 offset:3072
	s_add_u32 s8, s66, 0x80
	s_addc_u32 s9, s67, 0
	s_add_i32 s83, s76, 0x8000
	s_add_i32 s84, s76, 0xa000
	s_mov_b64 s[18:19], s[8:9]
	s_mov_b32 m0, s83
	s_add_u32 s8, s8, s20
	ds_read_b128 v[36:39], v141
	ds_read_b128 v[40:43], v141 offset:1024
	ds_read_b128 v[44:47], v141 offset:2048
	ds_read_b128 v[48:51], v141 offset:3072
	ds_read_b128 v[52:55], v141 offset:4096
	ds_read_b128 v[56:59], v141 offset:5120
	ds_read_b128 v[60:63], v141 offset:6144
	ds_read_b128 v[64:67], v141 offset:7168
	s_addc_u32 s9, s9, s21
	global_load_lds_dwordx4 v137, s[18:19]
	s_mov_b32 m0, s84
	s_add_i32 s85, s76, 0xc000
	global_load_lds_dwordx4 v136, s[18:19]
	s_mov_b32 m0, s85
	s_add_i32 s86, s76, 0xe000
	s_add_u32 s18, s16, 0x80
	global_load_lds_dwordx4 v137, s[8:9]
	s_mov_b32 m0, s86
	s_addc_u32 s19, s17, 0
	global_load_lds_dwordx4 v136, s[8:9]
	s_waitcnt vmcnt(8)
	s_waitcnt lgkmcnt(0)
	s_barrier
	s_setprio 1
	s_waitcnt lgkmcnt(0)
	v_mfma_f32_16x16x32_bf16 v[68:71], v[4:7], v[36:39], 0
	v_mfma_f32_16x16x32_bf16 v[72:75], v[12:15], v[36:39], 0
	v_mfma_f32_16x16x32_bf16 v[76:79], v[4:7], v[44:47], 0
	v_mfma_f32_16x16x32_bf16 v[80:83], v[12:15], v[44:47], 0
	v_mfma_f32_16x16x32_bf16 v[84:87], v[4:7], v[52:55], 0
	v_mfma_f32_16x16x32_bf16 v[88:91], v[12:15], v[52:55], 0
	v_mfma_f32_16x16x32_bf16 v[92:95], v[4:7], v[60:63], 0
	v_mfma_f32_16x16x32_bf16 v[96:99], v[12:15], v[60:63], 0
	v_mfma_f32_16x16x32_bf16 v[68:71], v[8:11], v[40:43], v[68:71]
	v_mfma_f32_16x16x32_bf16 v[72:75], v[16:19], v[40:43], v[72:75]
	v_mfma_f32_16x16x32_bf16 v[76:79], v[8:11], v[48:51], v[76:79]
	v_mfma_f32_16x16x32_bf16 v[80:83], v[16:19], v[48:51], v[80:83]
	v_mfma_f32_16x16x32_bf16 v[84:87], v[8:11], v[56:59], v[84:87]
	v_mfma_f32_16x16x32_bf16 v[88:91], v[16:19], v[56:59], v[88:91]
	v_mfma_f32_16x16x32_bf16 v[92:95], v[8:11], v[64:67], v[92:95]
	v_mfma_f32_16x16x32_bf16 v[96:99], v[16:19], v[64:67], v[96:99]
	s_setprio 0
	s_setprio 1
	v_mfma_f32_16x16x32_bf16 v[100:103], v[20:23], v[36:39], 0
	v_mfma_f32_16x16x32_bf16 v[36:39], v[28:31], v[36:39], 0
	v_mfma_f32_16x16x32_bf16 v[100:103], v[24:27], v[40:43], v[100:103]
	v_mfma_f32_16x16x32_bf16 v[40:43], v[32:35], v[40:43], v[36:39]
	v_mfma_f32_16x16x32_bf16 v[36:39], v[20:23], v[44:47], 0
	v_mfma_f32_16x16x32_bf16 v[104:107], v[24:27], v[48:51], v[36:39]
	v_mfma_f32_16x16x32_bf16 v[36:39], v[28:31], v[44:47], 0
	v_mfma_f32_16x16x32_bf16 v[48:51], v[32:35], v[48:51], v[36:39]
	v_mfma_f32_16x16x32_bf16 v[36:39], v[20:23], v[52:55], 0
	v_mfma_f32_16x16x32_bf16 v[108:111], v[24:27], v[56:59], v[36:39]
	v_mfma_f32_16x16x32_bf16 v[36:39], v[28:31], v[52:55], 0
	v_mfma_f32_16x16x32_bf16 v[56:59], v[32:35], v[56:59], v[36:39]
	v_mfma_f32_16x16x32_bf16 v[36:39], v[20:23], v[60:63], 0
	v_mfma_f32_16x16x32_bf16 v[112:115], v[24:27], v[64:67], v[36:39]
	v_mfma_f32_16x16x32_bf16 v[36:39], v[28:31], v[60:63], 0
	v_mfma_f32_16x16x32_bf16 v[64:67], v[32:35], v[64:67], v[36:39]
	s_setprio 0
	s_barrier
	s_add_i32 s87, s87, s73
	s_mov_b64 s[8:9], s[16:17]
	s_mov_b32 m0, s87
	s_add_i32 s88, s87, 0x2000
	s_nop 0
	ds_read_b128 v[36:39], v141 offset:16384
	ds_read_b128 v[44:47], v141 offset:17408
	ds_read_b128 v[52:55], v141 offset:18432
	ds_read_b128 v[60:63], v141 offset:19456
	ds_read_b128 v[116:119], v141 offset:20480
	ds_read_b128 v[120:123], v141 offset:21504
	ds_read_b128 v[124:127], v141 offset:22528
	ds_read_b128 v[128:131], v141 offset:23552
	s_nop 0
	global_load_lds_dwordx4 v143, s[8:9]
	s_mov_b32 m0, s88
	s_nop 0
	global_load_lds_dwordx4 v142, s[8:9]
	s_add_u32 s8, s16, s20
	s_addc_u32 s9, s17, s21
	s_add_i32 s89, s89, s73
	s_mov_b32 m0, s89
	s_add_i32 s90, s89, 0x2000
	s_nop 0
	global_load_lds_dwordx4 v143, s[8:9]
	s_mov_b32 m0, s90
	s_nop 0
	global_load_lds_dwordx4 v142, s[8:9]
	s_waitcnt vmcnt(6)
	s_waitcnt lgkmcnt(0)
	s_barrier
	s_setprio 1
	s_waitcnt lgkmcnt(0)
	v_mfma_f32_16x16x32_bf16 v[144:147], v[4:7], v[36:39], 0
	v_mfma_f32_16x16x32_bf16 v[152:155], v[4:7], v[52:55], 0
	v_mfma_f32_16x16x32_bf16 v[160:163], v[4:7], v[116:119], 0
	v_mfma_f32_16x16x32_bf16 v[4:7], v[4:7], v[124:127], 0
	v_mfma_f32_16x16x32_bf16 v[148:151], v[12:15], v[36:39], 0
	v_mfma_f32_16x16x32_bf16 v[156:159], v[12:15], v[52:55], 0
	v_mfma_f32_16x16x32_bf16 v[164:167], v[12:15], v[116:119], 0
	v_mfma_f32_16x16x32_bf16 v[168:171], v[8:11], v[128:131], v[4:7]
	v_mfma_f32_16x16x32_bf16 v[4:7], v[12:15], v[124:127], 0
	v_mfma_f32_16x16x32_bf16 v[144:147], v[8:11], v[44:47], v[144:147]
	v_mfma_f32_16x16x32_bf16 v[148:151], v[16:19], v[44:47], v[148:151]
	v_mfma_f32_16x16x32_bf16 v[152:155], v[8:11], v[60:63], v[152:155]
	v_mfma_f32_16x16x32_bf16 v[156:159], v[16:19], v[60:63], v[156:159]
	v_mfma_f32_16x16x32_bf16 v[160:163], v[8:11], v[120:123], v[160:163]
	v_mfma_f32_16x16x32_bf16 v[164:167], v[16:19], v[120:123], v[164:167]
	v_mfma_f32_16x16x32_bf16 v[172:175], v[16:19], v[128:131], v[4:7]
	s_setprio 0
	s_setprio 1
	v_mfma_f32_16x16x32_bf16 v[4:7], v[20:23], v[36:39], 0
	v_mfma_f32_16x16x32_bf16 v[176:179], v[24:27], v[44:47], v[4:7]
	v_mfma_f32_16x16x32_bf16 v[4:7], v[28:31], v[36:39], 0
	v_mfma_f32_16x16x32_bf16 v[180:183], v[32:35], v[44:47], v[4:7]
	v_mfma_f32_16x16x32_bf16 v[4:7], v[20:23], v[52:55], 0
	v_mfma_f32_16x16x32_bf16 v[184:187], v[24:27], v[60:63], v[4:7]
	v_mfma_f32_16x16x32_bf16 v[4:7], v[28:31], v[52:55], 0
	v_mfma_f32_16x16x32_bf16 v[188:191], v[32:35], v[60:63], v[4:7]
	v_mfma_f32_16x16x32_bf16 v[4:7], v[20:23], v[116:119], 0
	v_mfma_f32_16x16x32_bf16 v[192:195], v[24:27], v[120:123], v[4:7]
	v_mfma_f32_16x16x32_bf16 v[4:7], v[28:31], v[116:119], 0
	v_mfma_f32_16x16x32_bf16 v[120:123], v[32:35], v[120:123], v[4:7]
	v_mfma_f32_16x16x32_bf16 v[4:7], v[20:23], v[124:127], 0
	v_mfma_f32_16x16x32_bf16 v[196:199], v[24:27], v[128:131], v[4:7]
	v_mfma_f32_16x16x32_bf16 v[4:7], v[28:31], v[124:127], 0
	v_mfma_f32_16x16x32_bf16 v[128:131], v[32:35], v[128:131], v[4:7]
	s_setprio 0
	s_barrier
	s_add_i32 s16, 0, 0x18000
	s_add_i32 s91, 0, 0x1c000
	v_add_u32_e32 v134, s16, v140
	v_add_u32_e32 v135, s91, v140
	ds_read_b128 v[116:119], v134
	ds_read_b128 v[124:127], v134 offset:1024
	ds_read_b128 v[200:203], v134 offset:2048
	ds_read_b128 v[204:207], v134 offset:3072
	ds_read_b128 v[216:219], v135
	ds_read_b128 v[220:223], v135 offset:1024
	ds_read_b128 v[224:227], v135 offset:2048
	ds_read_b128 v[228:231], v135 offset:3072
	s_mov_b32 m0, s76
	s_mov_b64 s[8:9], s[68:69]
	ds_read_b128 v[44:47], v141 offset:32768
	ds_read_b128 v[52:55], v141 offset:33792
	ds_read_b128 v[60:63], v141 offset:34816
	ds_read_b128 v[232:235], v141 offset:35840
	ds_read_b128 v[236:239], v141 offset:36864
	ds_read_b128 v[242:245], v141 offset:37888
	ds_read_b128 v[246:249], v141 offset:38912
	ds_read_b128 v[250:253], v141 offset:39936
	s_nop 0
	global_load_lds_dwordx4 v137, s[8:9]
	s_mov_b32 m0, s77
	s_nop 0
	global_load_lds_dwordx4 v136, s[8:9]
	s_add_u32 s8, s68, s20
	s_addc_u32 s9, s69, s21
	s_mov_b32 m0, s78
	s_nop 0
	global_load_lds_dwordx4 v137, s[8:9]
	s_mov_b32 m0, s79
	s_nop 0
	global_load_lds_dwordx4 v136, s[8:9]
	s_waitcnt vmcnt(8)
	s_waitcnt lgkmcnt(0)
	s_barrier
	s_setprio 1
	s_waitcnt lgkmcnt(0)
	v_mfma_f32_16x16x32_bf16 v[4:7], v[116:119], v[44:47], v[68:71]
	v_mfma_f32_16x16x32_bf16 v[4:7], v[124:127], v[52:55], v[4:7]
	v_mfma_f32_16x16x32_bf16 v[8:11], v[200:203], v[44:47], v[72:75]
	v_mfma_f32_16x16x32_bf16 v[8:11], v[204:207], v[52:55], v[8:11]
	v_mfma_f32_16x16x32_bf16 v[12:15], v[116:119], v[60:63], v[76:79]
	v_mfma_f32_16x16x32_bf16 v[12:15], v[124:127], v[232:235], v[12:15]
	v_mfma_f32_16x16x32_bf16 v[16:19], v[200:203], v[60:63], v[80:83]
	v_mfma_f32_16x16x32_bf16 v[16:19], v[204:207], v[232:235], v[16:19]
	v_mfma_f32_16x16x32_bf16 v[20:23], v[116:119], v[236:239], v[84:87]
	v_mfma_f32_16x16x32_bf16 v[20:23], v[124:127], v[242:245], v[20:23]
	v_mfma_f32_16x16x32_bf16 v[24:27], v[200:203], v[236:239], v[88:91]
	v_mfma_f32_16x16x32_bf16 v[24:27], v[204:207], v[242:245], v[24:27]
	v_mfma_f32_16x16x32_bf16 v[28:31], v[116:119], v[246:249], v[92:95]
	v_mfma_f32_16x16x32_bf16 v[28:31], v[124:127], v[250:253], v[28:31]
	v_mfma_f32_16x16x32_bf16 v[32:35], v[200:203], v[246:249], v[96:99]
	v_mfma_f32_16x16x32_bf16 v[32:35], v[204:207], v[250:253], v[32:35]
	s_setprio 0
	s_setprio 1
	v_mfma_f32_16x16x32_bf16 v[36:39], v[216:219], v[44:47], v[100:103]
	v_mfma_f32_16x16x32_bf16 v[40:43], v[224:227], v[44:47], v[40:43]
	v_mfma_f32_16x16x32_bf16 v[36:39], v[220:223], v[52:55], v[36:39]
	v_mfma_f32_16x16x32_bf16 v[40:43], v[228:231], v[52:55], v[40:43]
	v_mfma_f32_16x16x32_bf16 v[44:47], v[216:219], v[60:63], v[104:107]
	v_mfma_f32_16x16x32_bf16 v[48:51], v[224:227], v[60:63], v[48:51]
	v_mfma_f32_16x16x32_bf16 v[52:55], v[216:219], v[236:239], v[108:111]
	v_mfma_f32_16x16x32_bf16 v[56:59], v[224:227], v[236:239], v[56:59]
	v_mfma_f32_16x16x32_bf16 v[60:63], v[216:219], v[246:249], v[112:115]
	v_mfma_f32_16x16x32_bf16 v[64:67], v[224:227], v[246:249], v[64:67]
	v_mfma_f32_16x16x32_bf16 v[44:47], v[220:223], v[232:235], v[44:47]
	v_mfma_f32_16x16x32_bf16 v[48:51], v[228:231], v[232:235], v[48:51]
	v_mfma_f32_16x16x32_bf16 v[52:55], v[220:223], v[242:245], v[52:55]
	v_mfma_f32_16x16x32_bf16 v[56:59], v[228:231], v[242:245], v[56:59]
	v_mfma_f32_16x16x32_bf16 v[60:63], v[220:223], v[250:253], v[60:63]
	v_mfma_f32_16x16x32_bf16 v[64:67], v[228:231], v[250:253], v[64:67]
	s_setprio 0
	s_barrier
	s_add_i32 s68, s16, s73
	s_mov_b64 s[8:9], s[18:19]
	s_mov_b32 m0, s68
	s_add_i32 s69, s68, 0x2000
	ds_read_b128 v[104:107], v141 offset:49152
	ds_read_b128 v[108:111], v141 offset:50176
	ds_read_b128 v[112:115], v141 offset:51200
	ds_read_b128 v[232:235], v141 offset:52224
	ds_read_b128 v[236:239], v141 offset:53248
	ds_read_b128 v[242:245], v141 offset:54272
	ds_read_b128 v[246:249], v141 offset:55296
	ds_read_b128 v[250:253], v141 offset:56320
	s_nop 0
	global_load_lds_dwordx4 v143, s[8:9]
	s_mov_b32 m0, s69
	s_nop 0
	global_load_lds_dwordx4 v142, s[8:9]
	s_add_u32 s8, s18, s20
	s_addc_u32 s9, s19, s21
	s_add_i32 s91, s91, s73
	s_mov_b32 m0, s91
	s_add_i32 s92, s91, 0x2000
	s_nop 0
	global_load_lds_dwordx4 v143, s[8:9]
	s_mov_b32 m0, s92
	s_nop 0
	global_load_lds_dwordx4 v142, s[8:9]
	s_waitcnt vmcnt(6)
	s_waitcnt lgkmcnt(0)
	s_barrier
	s_setprio 1
	s_waitcnt lgkmcnt(0)
	v_mfma_f32_16x16x32_bf16 v[68:71], v[116:119], v[104:107], v[144:147]
	v_mfma_f32_16x16x32_bf16 v[68:71], v[124:127], v[108:111], v[68:71]
	v_mfma_f32_16x16x32_bf16 v[72:75], v[200:203], v[104:107], v[148:151]
	v_mfma_f32_16x16x32_bf16 v[72:75], v[204:207], v[108:111], v[72:75]
	v_mfma_f32_16x16x32_bf16 v[76:79], v[116:119], v[112:115], v[152:155]
	v_mfma_f32_16x16x32_bf16 v[76:79], v[124:127], v[232:235], v[76:79]
	v_mfma_f32_16x16x32_bf16 v[80:83], v[200:203], v[112:115], v[156:159]
	v_mfma_f32_16x16x32_bf16 v[80:83], v[204:207], v[232:235], v[80:83]
	v_mfma_f32_16x16x32_bf16 v[84:87], v[116:119], v[236:239], v[160:163]
	v_mfma_f32_16x16x32_bf16 v[84:87], v[124:127], v[242:245], v[84:87]
	v_mfma_f32_16x16x32_bf16 v[88:91], v[200:203], v[236:239], v[164:167]
	v_mfma_f32_16x16x32_bf16 v[88:91], v[204:207], v[242:245], v[88:91]
	v_mfma_f32_16x16x32_bf16 v[92:95], v[116:119], v[246:249], v[168:171]
	v_mfma_f32_16x16x32_bf16 v[92:95], v[124:127], v[250:253], v[92:95]
	v_mfma_f32_16x16x32_bf16 v[96:99], v[200:203], v[246:249], v[172:175]
	v_mfma_f32_16x16x32_bf16 v[96:99], v[204:207], v[250:253], v[96:99]
	s_setprio 0
	s_setprio 1
	v_mfma_f32_16x16x32_bf16 v[100:103], v[216:219], v[104:107], v[176:179]
	v_mfma_f32_16x16x32_bf16 v[104:107], v[224:227], v[104:107], v[180:183]
	v_mfma_f32_16x16x32_bf16 v[100:103], v[220:223], v[108:111], v[100:103]
	v_mfma_f32_16x16x32_bf16 v[104:107], v[228:231], v[108:111], v[104:107]
	v_mfma_f32_16x16x32_bf16 v[108:111], v[216:219], v[112:115], v[184:187]
	v_mfma_f32_16x16x32_bf16 v[112:115], v[224:227], v[112:115], v[188:191]
	v_mfma_f32_16x16x32_bf16 v[116:119], v[216:219], v[236:239], v[192:195]
	v_mfma_f32_16x16x32_bf16 v[120:123], v[224:227], v[236:239], v[120:123]
	v_mfma_f32_16x16x32_bf16 v[124:127], v[216:219], v[246:249], v[196:199]
	v_mfma_f32_16x16x32_bf16 v[128:131], v[224:227], v[246:249], v[128:131]
	v_mfma_f32_16x16x32_bf16 v[108:111], v[220:223], v[232:235], v[108:111]
	v_mfma_f32_16x16x32_bf16 v[112:115], v[228:231], v[232:235], v[112:115]
	v_mfma_f32_16x16x32_bf16 v[116:119], v[220:223], v[242:245], v[116:119]
	v_mfma_f32_16x16x32_bf16 v[120:123], v[228:231], v[242:245], v[120:123]
	v_mfma_f32_16x16x32_bf16 v[124:127], v[220:223], v[250:253], v[124:127]
	v_mfma_f32_16x16x32_bf16 v[128:131], v[228:231], v[250:253], v[128:131]
	s_setprio 0
	s_barrier
	s_andn2_b64 vcc, exec, s[60:61]
	s_cbranch_vccnz .LBB0_1031
	s_add_u32 s93, s64, 0x200
	s_addc_u32 s94, s65, 0
	s_add_u32 s66, s66, 0x200
	s_addc_u32 s67, s67, 0
	s_mov_b32 s95, 4
	.p2align	6

.LBB0_1154:
	s_add_u32 s18, s52, 0x100
	s_addc_u32 s19, s53, 0
	s_add_u32 s16, s20, 0x100
	s_addc_u32 s17, s21, 0
	s_and_b64 s[8:9], s[46:47], exec
	s_cselect_b32 s17, s27, s17
	s_cselect_b32 s16, s26, s16
	s_add_i32 s72, 0, 0x10000
	s_and_b64 s[8:9], s[46:47], exec
	s_cselect_b32 s43, s51, s19
	s_cselect_b32 s42, s50, s18
	s_add_i32 s76, 0, 0x14000
	v_add_u32_e32 v132, s72, v243
	v_add_u32_e32 v133, s76, v243
	ds_read_b128 v[4:7], v132
	ds_read_b128 v[8:11], v132 offset:1024
	ds_read_b128 v[12:15], v132 offset:2048
	ds_read_b128 v[16:19], v132 offset:3072
	ds_read_b128 v[20:23], v133
	ds_read_b128 v[24:27], v133 offset:1024
	ds_read_b128 v[28:31], v133 offset:2048
	ds_read_b128 v[32:35], v133 offset:3072
	s_add_u32 s8, s52, 0x80
	s_addc_u32 s9, s53, 0
	s_add_i32 s66, s58, 0x8000
	s_add_i32 s67, s58, 0xa000
	s_mov_b64 s[18:19], s[8:9]
	s_mov_b32 m0, s66
	s_add_u32 s8, s8, s28
	ds_read_b128 v[36:39], v244 offset:8192
	ds_read_b128 v[40:43], v244 offset:9216
	ds_read_b128 v[44:47], v244 offset:10240
	ds_read_b128 v[48:51], v244 offset:11264
	ds_read_b128 v[52:55], v244 offset:12288
	ds_read_b128 v[56:59], v244 offset:13312
	ds_read_b128 v[60:63], v244 offset:14336
	ds_read_b128 v[64:67], v244 offset:15360
	s_addc_u32 s9, s9, s29
	global_load_lds_dwordx4 v238, s[18:19]
	s_mov_b32 m0, s67
	s_add_i32 s68, s58, 0xc000
	global_load_lds_dwordx4 v2, s[18:19]
	s_mov_b32 m0, s68
	s_add_i32 s69, s58, 0xe000
	s_add_u32 s18, s16, 0x80
	global_load_lds_dwordx4 v238, s[8:9]
	s_mov_b32 m0, s69
	s_addc_u32 s19, s17, 0
	global_load_lds_dwordx4 v2, s[8:9]
	s_waitcnt vmcnt(8)
	s_waitcnt lgkmcnt(0)
	s_barrier
	s_setprio 1
	s_waitcnt lgkmcnt(0)
	v_mfma_f32_16x16x32_bf16 v[68:71], v[4:7], v[36:39], 0
	v_mfma_f32_16x16x32_bf16 v[72:75], v[12:15], v[36:39], 0
	v_mfma_f32_16x16x32_bf16 v[76:79], v[4:7], v[44:47], 0
	v_mfma_f32_16x16x32_bf16 v[80:83], v[12:15], v[44:47], 0
	v_mfma_f32_16x16x32_bf16 v[84:87], v[4:7], v[52:55], 0
	v_mfma_f32_16x16x32_bf16 v[88:91], v[12:15], v[52:55], 0
	v_mfma_f32_16x16x32_bf16 v[92:95], v[4:7], v[60:63], 0
	v_mfma_f32_16x16x32_bf16 v[96:99], v[12:15], v[60:63], 0
	v_mfma_f32_16x16x32_bf16 v[68:71], v[8:11], v[40:43], v[68:71]
	v_mfma_f32_16x16x32_bf16 v[72:75], v[16:19], v[40:43], v[72:75]
	v_mfma_f32_16x16x32_bf16 v[76:79], v[8:11], v[48:51], v[76:79]
	v_mfma_f32_16x16x32_bf16 v[80:83], v[16:19], v[48:51], v[80:83]
	v_mfma_f32_16x16x32_bf16 v[84:87], v[8:11], v[56:59], v[84:87]
	v_mfma_f32_16x16x32_bf16 v[88:91], v[16:19], v[56:59], v[88:91]
	v_mfma_f32_16x16x32_bf16 v[92:95], v[8:11], v[64:67], v[92:95]
	v_mfma_f32_16x16x32_bf16 v[96:99], v[16:19], v[64:67], v[96:99]
	s_setprio 0
	s_setprio 1
	v_mfma_f32_16x16x32_bf16 v[100:103], v[20:23], v[36:39], 0
	v_mfma_f32_16x16x32_bf16 v[36:39], v[28:31], v[36:39], 0
	v_mfma_f32_16x16x32_bf16 v[100:103], v[24:27], v[40:43], v[100:103]
	v_mfma_f32_16x16x32_bf16 v[40:43], v[32:35], v[40:43], v[36:39]
	v_mfma_f32_16x16x32_bf16 v[36:39], v[20:23], v[44:47], 0
	v_mfma_f32_16x16x32_bf16 v[104:107], v[24:27], v[48:51], v[36:39]
	v_mfma_f32_16x16x32_bf16 v[36:39], v[28:31], v[44:47], 0
	v_mfma_f32_16x16x32_bf16 v[48:51], v[32:35], v[48:51], v[36:39]
	v_mfma_f32_16x16x32_bf16 v[36:39], v[20:23], v[52:55], 0
	v_mfma_f32_16x16x32_bf16 v[108:111], v[24:27], v[56:59], v[36:39]
	v_mfma_f32_16x16x32_bf16 v[36:39], v[28:31], v[52:55], 0
	v_mfma_f32_16x16x32_bf16 v[56:59], v[32:35], v[56:59], v[36:39]
	v_mfma_f32_16x16x32_bf16 v[36:39], v[20:23], v[60:63], 0
	v_mfma_f32_16x16x32_bf16 v[112:115], v[24:27], v[64:67], v[36:39]
	v_mfma_f32_16x16x32_bf16 v[36:39], v[28:31], v[60:63], 0
	v_mfma_f32_16x16x32_bf16 v[64:67], v[32:35], v[64:67], v[36:39]
	s_setprio 0
	s_barrier
	s_add_i32 s72, s72, s57
	s_mov_b64 s[8:9], s[16:17]
	s_mov_b32 m0, s72
	s_add_i32 s73, s72, 0x2000
	s_nop 0
	ds_read_b128 v[36:39], v244 offset:24576
	ds_read_b128 v[44:47], v244 offset:25600
	ds_read_b128 v[52:55], v244 offset:26624
	ds_read_b128 v[60:63], v244 offset:27648
	ds_read_b128 v[116:119], v244 offset:28672
	ds_read_b128 v[120:123], v244 offset:29696
	ds_read_b128 v[124:127], v244 offset:30720
	ds_read_b128 v[128:131], v244 offset:31744
	s_nop 0
	global_load_lds_dwordx4 v246, s[8:9]
	s_mov_b32 m0, s73
	s_nop 0
	global_load_lds_dwordx4 v245, s[8:9]
	s_add_u32 s8, s16, s28
	s_addc_u32 s9, s17, s29
	s_add_i32 s76, s76, s57
	s_mov_b32 m0, s76
	s_add_i32 s77, s76, 0x2000
	s_nop 0
	global_load_lds_dwordx4 v246, s[8:9]
	s_mov_b32 m0, s77
	s_nop 0
	global_load_lds_dwordx4 v245, s[8:9]
	s_waitcnt vmcnt(6)
	s_waitcnt lgkmcnt(0)
	s_barrier
	s_setprio 1
	s_waitcnt lgkmcnt(0)
	v_mfma_f32_16x16x32_bf16 v[134:137], v[4:7], v[36:39], 0
	v_mfma_f32_16x16x32_bf16 v[144:147], v[4:7], v[52:55], 0
	v_mfma_f32_16x16x32_bf16 v[152:155], v[4:7], v[116:119], 0
	v_mfma_f32_16x16x32_bf16 v[4:7], v[4:7], v[124:127], 0
	v_mfma_f32_16x16x32_bf16 v[140:143], v[12:15], v[36:39], 0
	v_mfma_f32_16x16x32_bf16 v[148:151], v[12:15], v[52:55], 0
	v_mfma_f32_16x16x32_bf16 v[156:159], v[12:15], v[116:119], 0
	v_mfma_f32_16x16x32_bf16 v[160:163], v[8:11], v[128:131], v[4:7]
	v_mfma_f32_16x16x32_bf16 v[4:7], v[12:15], v[124:127], 0
	v_mfma_f32_16x16x32_bf16 v[136:139], v[8:11], v[44:47], v[134:137]
	v_mfma_f32_16x16x32_bf16 v[140:143], v[16:19], v[44:47], v[140:143]
	v_mfma_f32_16x16x32_bf16 v[144:147], v[8:11], v[60:63], v[144:147]
	v_mfma_f32_16x16x32_bf16 v[148:151], v[16:19], v[60:63], v[148:151]
	v_mfma_f32_16x16x32_bf16 v[152:155], v[8:11], v[120:123], v[152:155]
	v_mfma_f32_16x16x32_bf16 v[156:159], v[16:19], v[120:123], v[156:159]
	v_mfma_f32_16x16x32_bf16 v[164:167], v[16:19], v[128:131], v[4:7]
	s_setprio 0
	s_setprio 1
	v_mfma_f32_16x16x32_bf16 v[4:7], v[20:23], v[36:39], 0
	v_mfma_f32_16x16x32_bf16 v[168:171], v[24:27], v[44:47], v[4:7]
	v_mfma_f32_16x16x32_bf16 v[4:7], v[28:31], v[36:39], 0
	v_mfma_f32_16x16x32_bf16 v[172:175], v[32:35], v[44:47], v[4:7]
	v_mfma_f32_16x16x32_bf16 v[4:7], v[20:23], v[52:55], 0
	v_mfma_f32_16x16x32_bf16 v[176:179], v[24:27], v[60:63], v[4:7]
	v_mfma_f32_16x16x32_bf16 v[4:7], v[28:31], v[52:55], 0
	v_mfma_f32_16x16x32_bf16 v[180:183], v[32:35], v[60:63], v[4:7]
	v_mfma_f32_16x16x32_bf16 v[4:7], v[20:23], v[116:119], 0
	v_mfma_f32_16x16x32_bf16 v[184:187], v[24:27], v[120:123], v[4:7]
	v_mfma_f32_16x16x32_bf16 v[4:7], v[28:31], v[116:119], 0
	v_mfma_f32_16x16x32_bf16 v[120:123], v[32:35], v[120:123], v[4:7]
	v_mfma_f32_16x16x32_bf16 v[4:7], v[20:23], v[124:127], 0
	v_mfma_f32_16x16x32_bf16 v[188:191], v[24:27], v[128:131], v[4:7]
	v_mfma_f32_16x16x32_bf16 v[4:7], v[28:31], v[124:127], 0
	v_mfma_f32_16x16x32_bf16 v[128:131], v[32:35], v[128:131], v[4:7]
	s_setprio 0
	s_barrier
	s_add_i32 s16, 0, 0x18000
	s_add_i32 s78, 0, 0x1c000
	v_add_u32_e32 v134, s16, v243
	v_add_u32_e32 v135, s78, v243
	ds_read_b128 v[116:119], v134
	ds_read_b128 v[124:127], v134 offset:1024
	ds_read_b128 v[192:195], v134 offset:2048
	ds_read_b128 v[196:199], v134 offset:3072
	ds_read_b128 v[200:203], v135
	ds_read_b128 v[204:207], v135 offset:1024
	ds_read_b128 v[208:211], v135 offset:2048
	ds_read_b128 v[216:219], v135 offset:3072
	s_mov_b32 m0, s58
	s_mov_b64 s[8:9], s[42:43]
	ds_read_b128 v[44:47], v244 offset:40960
	ds_read_b128 v[52:55], v244 offset:41984
	ds_read_b128 v[60:63], v244 offset:43008
	ds_read_b128 v[220:223], v244 offset:44032
	ds_read_b128 v[224:227], v244 offset:45056
	ds_read_b128 v[228:231], v244 offset:46080
	ds_read_b128 v[232:235], v244 offset:47104
	ds_read_b128 v[248:251], v244 offset:48128
	s_nop 0
	global_load_lds_dwordx4 v238, s[8:9]
	s_mov_b32 m0, s59
	s_nop 0
	global_load_lds_dwordx4 v2, s[8:9]
	s_add_u32 s8, s42, s28
	s_addc_u32 s9, s43, s29
	s_mov_b32 m0, s60
	s_nop 0
	global_load_lds_dwordx4 v238, s[8:9]
	s_mov_b32 m0, s61
	s_nop 0
	global_load_lds_dwordx4 v2, s[8:9]
	s_waitcnt vmcnt(8)
	s_waitcnt lgkmcnt(0)
	s_barrier
	s_setprio 1
	s_waitcnt lgkmcnt(0)
	v_mfma_f32_16x16x32_bf16 v[4:7], v[116:119], v[44:47], v[68:71]
	v_mfma_f32_16x16x32_bf16 v[4:7], v[124:127], v[52:55], v[4:7]
	v_mfma_f32_16x16x32_bf16 v[8:11], v[192:195], v[44:47], v[72:75]
	v_mfma_f32_16x16x32_bf16 v[8:11], v[196:199], v[52:55], v[8:11]
	v_mfma_f32_16x16x32_bf16 v[12:15], v[116:119], v[60:63], v[76:79]
	v_mfma_f32_16x16x32_bf16 v[12:15], v[124:127], v[220:223], v[12:15]
	v_mfma_f32_16x16x32_bf16 v[16:19], v[192:195], v[60:63], v[80:83]
	v_mfma_f32_16x16x32_bf16 v[16:19], v[196:199], v[220:223], v[16:19]
	v_mfma_f32_16x16x32_bf16 v[20:23], v[116:119], v[224:227], v[84:87]
	v_mfma_f32_16x16x32_bf16 v[20:23], v[124:127], v[228:231], v[20:23]
	v_mfma_f32_16x16x32_bf16 v[24:27], v[192:195], v[224:227], v[88:91]
	v_mfma_f32_16x16x32_bf16 v[24:27], v[196:199], v[228:231], v[24:27]
	v_mfma_f32_16x16x32_bf16 v[28:31], v[116:119], v[232:235], v[92:95]
	v_mfma_f32_16x16x32_bf16 v[28:31], v[124:127], v[248:251], v[28:31]
	v_mfma_f32_16x16x32_bf16 v[32:35], v[192:195], v[232:235], v[96:99]
	v_mfma_f32_16x16x32_bf16 v[32:35], v[196:199], v[248:251], v[32:35]
	s_setprio 0
	s_setprio 1
	v_mfma_f32_16x16x32_bf16 v[36:39], v[200:203], v[44:47], v[100:103]
	v_mfma_f32_16x16x32_bf16 v[40:43], v[208:211], v[44:47], v[40:43]
	v_mfma_f32_16x16x32_bf16 v[36:39], v[204:207], v[52:55], v[36:39]
	v_mfma_f32_16x16x32_bf16 v[40:43], v[216:219], v[52:55], v[40:43]
	v_mfma_f32_16x16x32_bf16 v[44:47], v[200:203], v[60:63], v[104:107]
	v_mfma_f32_16x16x32_bf16 v[48:51], v[208:211], v[60:63], v[48:51]
	v_mfma_f32_16x16x32_bf16 v[52:55], v[200:203], v[224:227], v[108:111]
	v_mfma_f32_16x16x32_bf16 v[56:59], v[208:211], v[224:227], v[56:59]
	v_mfma_f32_16x16x32_bf16 v[60:63], v[200:203], v[232:235], v[112:115]
	v_mfma_f32_16x16x32_bf16 v[64:67], v[208:211], v[232:235], v[64:67]
	v_mfma_f32_16x16x32_bf16 v[44:47], v[204:207], v[220:223], v[44:47]
	v_mfma_f32_16x16x32_bf16 v[48:51], v[216:219], v[220:223], v[48:51]
	v_mfma_f32_16x16x32_bf16 v[52:55], v[204:207], v[228:231], v[52:55]
	v_mfma_f32_16x16x32_bf16 v[56:59], v[216:219], v[228:231], v[56:59]
	v_mfma_f32_16x16x32_bf16 v[60:63], v[204:207], v[248:251], v[60:63]
	v_mfma_f32_16x16x32_bf16 v[64:67], v[216:219], v[248:251], v[64:67]
	s_setprio 0
	s_barrier
	s_add_i32 s42, s16, s57
	s_mov_b64 s[8:9], s[18:19]
	s_mov_b32 m0, s42
	s_add_i32 s43, s42, 0x2000
	ds_read_b128 v[104:107], v244 offset:57344
	ds_read_b128 v[108:111], v244 offset:58368
	ds_read_b128 v[112:115], v244 offset:59392
	ds_read_b128 v[220:223], v244 offset:60416
	ds_read_b128 v[224:227], v244 offset:61440
	ds_read_b128 v[228:231], v244 offset:62464
	ds_read_b128 v[232:235], v244 offset:63488
	ds_read_b128 v[248:251], v244 offset:64512
	s_nop 0
	global_load_lds_dwordx4 v246, s[8:9]
	s_mov_b32 m0, s43
	s_nop 0
	global_load_lds_dwordx4 v245, s[8:9]
	s_add_u32 s8, s18, s28
	s_addc_u32 s9, s19, s29
	s_add_i32 s78, s78, s57
	s_mov_b32 m0, s78
	s_add_i32 s79, s78, 0x2000
	s_nop 0
	global_load_lds_dwordx4 v246, s[8:9]
	s_mov_b32 m0, s79
	s_nop 0
	global_load_lds_dwordx4 v245, s[8:9]
	s_waitcnt vmcnt(6)
	s_waitcnt lgkmcnt(0)
	s_barrier
	s_setprio 1
	s_waitcnt lgkmcnt(0)
	v_mfma_f32_16x16x32_bf16 v[68:71], v[116:119], v[104:107], v[136:139]
	v_mfma_f32_16x16x32_bf16 v[68:71], v[124:127], v[108:111], v[68:71]
	v_mfma_f32_16x16x32_bf16 v[72:75], v[192:195], v[104:107], v[140:143]
	v_mfma_f32_16x16x32_bf16 v[72:75], v[196:199], v[108:111], v[72:75]
	v_mfma_f32_16x16x32_bf16 v[76:79], v[116:119], v[112:115], v[144:147]
	v_mfma_f32_16x16x32_bf16 v[76:79], v[124:127], v[220:223], v[76:79]
	v_mfma_f32_16x16x32_bf16 v[80:83], v[192:195], v[112:115], v[148:151]
	v_mfma_f32_16x16x32_bf16 v[80:83], v[196:199], v[220:223], v[80:83]
	v_mfma_f32_16x16x32_bf16 v[84:87], v[116:119], v[224:227], v[152:155]
	v_mfma_f32_16x16x32_bf16 v[84:87], v[124:127], v[228:231], v[84:87]
	v_mfma_f32_16x16x32_bf16 v[88:91], v[192:195], v[224:227], v[156:159]
	v_mfma_f32_16x16x32_bf16 v[88:91], v[196:199], v[228:231], v[88:91]
	v_mfma_f32_16x16x32_bf16 v[92:95], v[116:119], v[232:235], v[160:163]
	v_mfma_f32_16x16x32_bf16 v[92:95], v[124:127], v[248:251], v[92:95]
	v_mfma_f32_16x16x32_bf16 v[96:99], v[192:195], v[232:235], v[164:167]
	v_mfma_f32_16x16x32_bf16 v[96:99], v[196:199], v[248:251], v[96:99]
	s_setprio 0
	s_setprio 1
	v_mfma_f32_16x16x32_bf16 v[100:103], v[200:203], v[104:107], v[168:171]
	v_mfma_f32_16x16x32_bf16 v[104:107], v[208:211], v[104:107], v[172:175]
	v_mfma_f32_16x16x32_bf16 v[100:103], v[204:207], v[108:111], v[100:103]
	v_mfma_f32_16x16x32_bf16 v[104:107], v[216:219], v[108:111], v[104:107]
	v_mfma_f32_16x16x32_bf16 v[108:111], v[200:203], v[112:115], v[176:179]
	v_mfma_f32_16x16x32_bf16 v[112:115], v[208:211], v[112:115], v[180:183]
	v_mfma_f32_16x16x32_bf16 v[116:119], v[200:203], v[224:227], v[184:187]
	v_mfma_f32_16x16x32_bf16 v[120:123], v[208:211], v[224:227], v[120:123]
	v_mfma_f32_16x16x32_bf16 v[124:127], v[200:203], v[232:235], v[188:191]
	v_mfma_f32_16x16x32_bf16 v[128:131], v[208:211], v[232:235], v[128:131]
	v_mfma_f32_16x16x32_bf16 v[108:111], v[204:207], v[220:223], v[108:111]
	v_mfma_f32_16x16x32_bf16 v[112:115], v[216:219], v[220:223], v[112:115]
	v_mfma_f32_16x16x32_bf16 v[116:119], v[204:207], v[228:231], v[116:119]
	v_mfma_f32_16x16x32_bf16 v[120:123], v[216:219], v[228:231], v[120:123]
	v_mfma_f32_16x16x32_bf16 v[124:127], v[204:207], v[248:251], v[124:127]
	v_mfma_f32_16x16x32_bf16 v[128:131], v[216:219], v[248:251], v[128:131]
	s_setprio 0
	s_barrier
	s_andn2_b64 vcc, exec, s[48:49]
	s_cbranch_vccnz .LBB0_1157
	s_add_u32 s80, s20, 0x200
	s_addc_u32 s81, s21, 0
	s_add_u32 s52, s52, 0x200
	s_addc_u32 s53, s53, 0
	s_mov_b32 s82, 4
	.p2align	6

.LBB0_1174:
	s_add_u32 s18, s50, 0x100
	s_addc_u32 s19, s51, 0
	s_add_u32 s16, s26, 0x100
	s_addc_u32 s17, s27, 0
	s_and_b64 s[8:9], s[46:47], exec
	s_cselect_b32 s17, s21, s17
	s_cselect_b32 s16, s20, s16
	s_add_i32 s68, 0, 0x10000
	s_and_b64 s[8:9], s[46:47], exec
	s_cselect_b32 s43, s41, s19
	s_cselect_b32 s42, s40, s18
	s_add_i32 s72, 0, 0x14000
	v_add_u32_e32 v132, s68, v243
	v_add_u32_e32 v133, s72, v243
	ds_read_b128 v[4:7], v132
	ds_read_b128 v[8:11], v132 offset:1024
	ds_read_b128 v[12:15], v132 offset:2048
	ds_read_b128 v[16:19], v132 offset:3072
	ds_read_b128 v[20:23], v133
	ds_read_b128 v[24:27], v133 offset:1024
	ds_read_b128 v[28:31], v133 offset:2048
	ds_read_b128 v[32:35], v133 offset:3072
	s_add_u32 s8, s50, 0x80
	s_addc_u32 s9, s51, 0
	s_add_i32 s64, s53, 0x8000
	s_add_i32 s65, s53, 0xa000
	s_mov_b64 s[18:19], s[8:9]
	s_mov_b32 m0, s64
	s_add_u32 s8, s8, s28
	ds_read_b128 v[36:39], v244
	ds_read_b128 v[40:43], v244 offset:1024
	ds_read_b128 v[44:47], v244 offset:2048
	ds_read_b128 v[48:51], v244 offset:3072
	ds_read_b128 v[52:55], v244 offset:4096
	ds_read_b128 v[56:59], v244 offset:5120
	ds_read_b128 v[60:63], v244 offset:6144
	ds_read_b128 v[64:67], v244 offset:7168
	s_addc_u32 s9, s9, s29
	global_load_lds_dwordx4 v238, s[18:19]
	s_mov_b32 m0, s65
	s_add_i32 s66, s53, 0xc000
	global_load_lds_dwordx4 v2, s[18:19]
	s_mov_b32 m0, s66
	s_add_i32 s67, s53, 0xe000
	s_add_u32 s18, s16, 0x80
	global_load_lds_dwordx4 v238, s[8:9]
	s_mov_b32 m0, s67
	s_addc_u32 s19, s17, 0
	global_load_lds_dwordx4 v2, s[8:9]
	s_waitcnt vmcnt(8)
	s_waitcnt lgkmcnt(0)
	s_barrier
	s_setprio 1
	s_waitcnt lgkmcnt(0)
	v_mfma_f32_16x16x32_bf16 v[68:71], v[4:7], v[36:39], 0
	v_mfma_f32_16x16x32_bf16 v[72:75], v[12:15], v[36:39], 0
	v_mfma_f32_16x16x32_bf16 v[76:79], v[4:7], v[44:47], 0
	v_mfma_f32_16x16x32_bf16 v[80:83], v[12:15], v[44:47], 0
	v_mfma_f32_16x16x32_bf16 v[84:87], v[4:7], v[52:55], 0
	v_mfma_f32_16x16x32_bf16 v[88:91], v[12:15], v[52:55], 0
	v_mfma_f32_16x16x32_bf16 v[92:95], v[4:7], v[60:63], 0
	v_mfma_f32_16x16x32_bf16 v[96:99], v[12:15], v[60:63], 0
	v_mfma_f32_16x16x32_bf16 v[68:71], v[8:11], v[40:43], v[68:71]
	v_mfma_f32_16x16x32_bf16 v[72:75], v[16:19], v[40:43], v[72:75]
	v_mfma_f32_16x16x32_bf16 v[76:79], v[8:11], v[48:51], v[76:79]
	v_mfma_f32_16x16x32_bf16 v[80:83], v[16:19], v[48:51], v[80:83]
	v_mfma_f32_16x16x32_bf16 v[84:87], v[8:11], v[56:59], v[84:87]
	v_mfma_f32_16x16x32_bf16 v[88:91], v[16:19], v[56:59], v[88:91]
	v_mfma_f32_16x16x32_bf16 v[92:95], v[8:11], v[64:67], v[92:95]
	v_mfma_f32_16x16x32_bf16 v[96:99], v[16:19], v[64:67], v[96:99]
	s_setprio 0
	s_setprio 1
	v_mfma_f32_16x16x32_bf16 v[100:103], v[20:23], v[36:39], 0
	v_mfma_f32_16x16x32_bf16 v[36:39], v[28:31], v[36:39], 0
	v_mfma_f32_16x16x32_bf16 v[100:103], v[24:27], v[40:43], v[100:103]
	v_mfma_f32_16x16x32_bf16 v[40:43], v[32:35], v[40:43], v[36:39]
	v_mfma_f32_16x16x32_bf16 v[36:39], v[20:23], v[44:47], 0
	v_mfma_f32_16x16x32_bf16 v[104:107], v[24:27], v[48:51], v[36:39]
	v_mfma_f32_16x16x32_bf16 v[36:39], v[28:31], v[44:47], 0
	v_mfma_f32_16x16x32_bf16 v[48:51], v[32:35], v[48:51], v[36:39]
	v_mfma_f32_16x16x32_bf16 v[36:39], v[20:23], v[52:55], 0
	v_mfma_f32_16x16x32_bf16 v[108:111], v[24:27], v[56:59], v[36:39]
	v_mfma_f32_16x16x32_bf16 v[36:39], v[28:31], v[52:55], 0
	v_mfma_f32_16x16x32_bf16 v[56:59], v[32:35], v[56:59], v[36:39]
	v_mfma_f32_16x16x32_bf16 v[36:39], v[20:23], v[60:63], 0
	v_mfma_f32_16x16x32_bf16 v[112:115], v[24:27], v[64:67], v[36:39]
	v_mfma_f32_16x16x32_bf16 v[36:39], v[28:31], v[60:63], 0
	v_mfma_f32_16x16x32_bf16 v[64:67], v[32:35], v[64:67], v[36:39]
	s_setprio 0
	s_barrier
	s_add_i32 s68, s68, s52
	s_mov_b64 s[8:9], s[16:17]
	s_mov_b32 m0, s68
	s_add_i32 s69, s68, 0x2000
	s_nop 0
	ds_read_b128 v[36:39], v244 offset:16384
	ds_read_b128 v[44:47], v244 offset:17408
	ds_read_b128 v[52:55], v244 offset:18432
	ds_read_b128 v[60:63], v244 offset:19456
	ds_read_b128 v[116:119], v244 offset:20480
	ds_read_b128 v[120:123], v244 offset:21504
	ds_read_b128 v[124:127], v244 offset:22528
	ds_read_b128 v[128:131], v244 offset:23552
	s_nop 0
	global_load_lds_dwordx4 v246, s[8:9]
	s_mov_b32 m0, s69
	s_nop 0
	global_load_lds_dwordx4 v245, s[8:9]
	s_add_u32 s8, s16, s28
	s_addc_u32 s9, s17, s29
	s_add_i32 s72, s72, s52
	s_mov_b32 m0, s72
	s_add_i32 s73, s72, 0x2000
	s_nop 0
	global_load_lds_dwordx4 v246, s[8:9]
	s_mov_b32 m0, s73
	s_nop 0
	global_load_lds_dwordx4 v245, s[8:9]
	s_waitcnt vmcnt(6)
	s_waitcnt lgkmcnt(0)
	s_barrier
	s_setprio 1
	s_waitcnt lgkmcnt(0)
	v_mfma_f32_16x16x32_bf16 v[134:137], v[4:7], v[36:39], 0
	v_mfma_f32_16x16x32_bf16 v[144:147], v[4:7], v[52:55], 0
	v_mfma_f32_16x16x32_bf16 v[152:155], v[4:7], v[116:119], 0
	v_mfma_f32_16x16x32_bf16 v[4:7], v[4:7], v[124:127], 0
	v_mfma_f32_16x16x32_bf16 v[140:143], v[12:15], v[36:39], 0
	v_mfma_f32_16x16x32_bf16 v[148:151], v[12:15], v[52:55], 0
	v_mfma_f32_16x16x32_bf16 v[156:159], v[12:15], v[116:119], 0
	v_mfma_f32_16x16x32_bf16 v[160:163], v[8:11], v[128:131], v[4:7]
	v_mfma_f32_16x16x32_bf16 v[4:7], v[12:15], v[124:127], 0
	v_mfma_f32_16x16x32_bf16 v[136:139], v[8:11], v[44:47], v[134:137]
	v_mfma_f32_16x16x32_bf16 v[140:143], v[16:19], v[44:47], v[140:143]
	v_mfma_f32_16x16x32_bf16 v[144:147], v[8:11], v[60:63], v[144:147]
	v_mfma_f32_16x16x32_bf16 v[148:151], v[16:19], v[60:63], v[148:151]
	v_mfma_f32_16x16x32_bf16 v[152:155], v[8:11], v[120:123], v[152:155]
	v_mfma_f32_16x16x32_bf16 v[156:159], v[16:19], v[120:123], v[156:159]
	v_mfma_f32_16x16x32_bf16 v[164:167], v[16:19], v[128:131], v[4:7]
	s_setprio 0
	s_setprio 1
	v_mfma_f32_16x16x32_bf16 v[4:7], v[20:23], v[36:39], 0
	v_mfma_f32_16x16x32_bf16 v[168:171], v[24:27], v[44:47], v[4:7]
	v_mfma_f32_16x16x32_bf16 v[4:7], v[28:31], v[36:39], 0
	v_mfma_f32_16x16x32_bf16 v[172:175], v[32:35], v[44:47], v[4:7]
	v_mfma_f32_16x16x32_bf16 v[4:7], v[20:23], v[52:55], 0
	v_mfma_f32_16x16x32_bf16 v[176:179], v[24:27], v[60:63], v[4:7]
	v_mfma_f32_16x16x32_bf16 v[4:7], v[28:31], v[52:55], 0
	v_mfma_f32_16x16x32_bf16 v[180:183], v[32:35], v[60:63], v[4:7]
	v_mfma_f32_16x16x32_bf16 v[4:7], v[20:23], v[116:119], 0
	v_mfma_f32_16x16x32_bf16 v[184:187], v[24:27], v[120:123], v[4:7]
	v_mfma_f32_16x16x32_bf16 v[4:7], v[28:31], v[116:119], 0
	v_mfma_f32_16x16x32_bf16 v[120:123], v[32:35], v[120:123], v[4:7]
	v_mfma_f32_16x16x32_bf16 v[4:7], v[20:23], v[124:127], 0
	v_mfma_f32_16x16x32_bf16 v[188:191], v[24:27], v[128:131], v[4:7]
	v_mfma_f32_16x16x32_bf16 v[4:7], v[28:31], v[124:127], 0
	v_mfma_f32_16x16x32_bf16 v[128:131], v[32:35], v[128:131], v[4:7]
	s_setprio 0
	s_barrier
	s_add_i32 s16, 0, 0x18000
	s_add_i32 s76, 0, 0x1c000
	v_add_u32_e32 v134, s16, v243
	v_add_u32_e32 v135, s76, v243
	ds_read_b128 v[116:119], v134
	ds_read_b128 v[124:127], v134 offset:1024
	ds_read_b128 v[192:195], v134 offset:2048
	ds_read_b128 v[196:199], v134 offset:3072
	ds_read_b128 v[200:203], v135
	ds_read_b128 v[204:207], v135 offset:1024
	ds_read_b128 v[216:219], v135 offset:2048
	ds_read_b128 v[220:223], v135 offset:3072
	s_mov_b32 m0, s53
	s_mov_b64 s[8:9], s[42:43]
	ds_read_b128 v[44:47], v244 offset:32768
	ds_read_b128 v[52:55], v244 offset:33792
	ds_read_b128 v[60:63], v244 offset:34816
	ds_read_b128 v[224:227], v244 offset:35840
	ds_read_b128 v[228:231], v244 offset:36864
	ds_read_b128 v[232:235], v244 offset:37888
	ds_read_b128 v[248:251], v244 offset:38912
	ds_read_b128 v[208:211], v244 offset:39936
	s_nop 0
	global_load_lds_dwordx4 v238, s[8:9]
	s_mov_b32 m0, s57
	s_nop 0
	global_load_lds_dwordx4 v2, s[8:9]
	s_add_u32 s8, s42, s28
	s_addc_u32 s9, s43, s29
	s_mov_b32 m0, s58
	s_nop 0
	global_load_lds_dwordx4 v238, s[8:9]
	s_mov_b32 m0, s59
	s_nop 0
	global_load_lds_dwordx4 v2, s[8:9]
	s_waitcnt vmcnt(8)
	s_waitcnt lgkmcnt(0)
	s_barrier
	s_setprio 1
	s_waitcnt lgkmcnt(0)
	v_mfma_f32_16x16x32_bf16 v[4:7], v[116:119], v[44:47], v[68:71]
	v_mfma_f32_16x16x32_bf16 v[4:7], v[124:127], v[52:55], v[4:7]
	v_mfma_f32_16x16x32_bf16 v[8:11], v[192:195], v[44:47], v[72:75]
	v_mfma_f32_16x16x32_bf16 v[8:11], v[196:199], v[52:55], v[8:11]
	v_mfma_f32_16x16x32_bf16 v[12:15], v[116:119], v[60:63], v[76:79]
	v_mfma_f32_16x16x32_bf16 v[12:15], v[124:127], v[224:227], v[12:15]
	v_mfma_f32_16x16x32_bf16 v[16:19], v[192:195], v[60:63], v[80:83]
	v_mfma_f32_16x16x32_bf16 v[16:19], v[196:199], v[224:227], v[16:19]
	v_mfma_f32_16x16x32_bf16 v[20:23], v[116:119], v[228:231], v[84:87]
	v_mfma_f32_16x16x32_bf16 v[20:23], v[124:127], v[232:235], v[20:23]
	v_mfma_f32_16x16x32_bf16 v[24:27], v[192:195], v[228:231], v[88:91]
	v_mfma_f32_16x16x32_bf16 v[24:27], v[196:199], v[232:235], v[24:27]
	v_mfma_f32_16x16x32_bf16 v[28:31], v[116:119], v[248:251], v[92:95]
	v_mfma_f32_16x16x32_bf16 v[28:31], v[124:127], v[208:211], v[28:31]
	v_mfma_f32_16x16x32_bf16 v[32:35], v[192:195], v[248:251], v[96:99]
	v_mfma_f32_16x16x32_bf16 v[32:35], v[196:199], v[208:211], v[32:35]
	s_setprio 0
	s_setprio 1
	v_mfma_f32_16x16x32_bf16 v[36:39], v[200:203], v[44:47], v[100:103]
	v_mfma_f32_16x16x32_bf16 v[40:43], v[216:219], v[44:47], v[40:43]
	v_mfma_f32_16x16x32_bf16 v[36:39], v[204:207], v[52:55], v[36:39]
	v_mfma_f32_16x16x32_bf16 v[40:43], v[220:223], v[52:55], v[40:43]
	v_mfma_f32_16x16x32_bf16 v[44:47], v[200:203], v[60:63], v[104:107]
	v_mfma_f32_16x16x32_bf16 v[48:51], v[216:219], v[60:63], v[48:51]
	v_mfma_f32_16x16x32_bf16 v[52:55], v[200:203], v[228:231], v[108:111]
	v_mfma_f32_16x16x32_bf16 v[56:59], v[216:219], v[228:231], v[56:59]
	v_mfma_f32_16x16x32_bf16 v[60:63], v[200:203], v[248:251], v[112:115]
	v_mfma_f32_16x16x32_bf16 v[64:67], v[216:219], v[248:251], v[64:67]
	v_mfma_f32_16x16x32_bf16 v[44:47], v[204:207], v[224:227], v[44:47]
	v_mfma_f32_16x16x32_bf16 v[48:51], v[220:223], v[224:227], v[48:51]
	v_mfma_f32_16x16x32_bf16 v[52:55], v[204:207], v[232:235], v[52:55]
	v_mfma_f32_16x16x32_bf16 v[56:59], v[220:223], v[232:235], v[56:59]
	v_mfma_f32_16x16x32_bf16 v[60:63], v[204:207], v[208:211], v[60:63]
	v_mfma_f32_16x16x32_bf16 v[64:67], v[220:223], v[208:211], v[64:67]
	s_setprio 0
	s_barrier
	s_add_i32 s42, s16, s52
	s_mov_b64 s[8:9], s[18:19]
	s_mov_b32 m0, s42
	s_add_i32 s43, s42, 0x2000
	ds_read_b128 v[104:107], v244 offset:49152
	ds_read_b128 v[108:111], v244 offset:50176
	ds_read_b128 v[112:115], v244 offset:51200
	ds_read_b128 v[208:211], v244 offset:52224
	ds_read_b128 v[224:227], v244 offset:53248
	ds_read_b128 v[228:231], v244 offset:54272
	ds_read_b128 v[232:235], v244 offset:55296
	ds_read_b128 v[248:251], v244 offset:56320
	s_nop 0
	global_load_lds_dwordx4 v246, s[8:9]
	s_mov_b32 m0, s43
	s_nop 0
	global_load_lds_dwordx4 v245, s[8:9]
	s_add_u32 s8, s18, s28
	s_addc_u32 s9, s19, s29
	s_add_i32 s76, s76, s52
	s_mov_b32 m0, s76
	s_add_i32 s77, s76, 0x2000
	s_nop 0
	global_load_lds_dwordx4 v246, s[8:9]
	s_mov_b32 m0, s77
	s_nop 0
	global_load_lds_dwordx4 v245, s[8:9]
	s_waitcnt vmcnt(6)
	s_waitcnt lgkmcnt(0)
	s_barrier
	s_setprio 1
	s_waitcnt lgkmcnt(0)
	v_mfma_f32_16x16x32_bf16 v[68:71], v[116:119], v[104:107], v[136:139]
	v_mfma_f32_16x16x32_bf16 v[68:71], v[124:127], v[108:111], v[68:71]
	v_mfma_f32_16x16x32_bf16 v[72:75], v[192:195], v[104:107], v[140:143]
	v_mfma_f32_16x16x32_bf16 v[72:75], v[196:199], v[108:111], v[72:75]
	v_mfma_f32_16x16x32_bf16 v[76:79], v[116:119], v[112:115], v[144:147]
	v_mfma_f32_16x16x32_bf16 v[76:79], v[124:127], v[208:211], v[76:79]
	v_mfma_f32_16x16x32_bf16 v[80:83], v[192:195], v[112:115], v[148:151]
	v_mfma_f32_16x16x32_bf16 v[80:83], v[196:199], v[208:211], v[80:83]
	v_mfma_f32_16x16x32_bf16 v[84:87], v[116:119], v[224:227], v[152:155]
	v_mfma_f32_16x16x32_bf16 v[84:87], v[124:127], v[228:231], v[84:87]
	v_mfma_f32_16x16x32_bf16 v[88:91], v[192:195], v[224:227], v[156:159]
	v_mfma_f32_16x16x32_bf16 v[88:91], v[196:199], v[228:231], v[88:91]
	v_mfma_f32_16x16x32_bf16 v[92:95], v[116:119], v[232:235], v[160:163]
	v_mfma_f32_16x16x32_bf16 v[92:95], v[124:127], v[248:251], v[92:95]
	v_mfma_f32_16x16x32_bf16 v[96:99], v[192:195], v[232:235], v[164:167]
	v_mfma_f32_16x16x32_bf16 v[96:99], v[196:199], v[248:251], v[96:99]
	s_setprio 0
	s_setprio 1
	v_mfma_f32_16x16x32_bf16 v[100:103], v[200:203], v[104:107], v[168:171]
	v_mfma_f32_16x16x32_bf16 v[104:107], v[216:219], v[104:107], v[172:175]
	v_mfma_f32_16x16x32_bf16 v[100:103], v[204:207], v[108:111], v[100:103]
	v_mfma_f32_16x16x32_bf16 v[104:107], v[220:223], v[108:111], v[104:107]
	v_mfma_f32_16x16x32_bf16 v[108:111], v[200:203], v[112:115], v[176:179]
	v_mfma_f32_16x16x32_bf16 v[112:115], v[216:219], v[112:115], v[180:183]
	v_mfma_f32_16x16x32_bf16 v[116:119], v[200:203], v[224:227], v[184:187]
	v_mfma_f32_16x16x32_bf16 v[120:123], v[216:219], v[224:227], v[120:123]
	v_mfma_f32_16x16x32_bf16 v[124:127], v[200:203], v[232:235], v[188:191]
	v_mfma_f32_16x16x32_bf16 v[128:131], v[216:219], v[232:235], v[128:131]
	v_mfma_f32_16x16x32_bf16 v[108:111], v[204:207], v[208:211], v[108:111]
	v_mfma_f32_16x16x32_bf16 v[112:115], v[220:223], v[208:211], v[112:115]
	v_mfma_f32_16x16x32_bf16 v[116:119], v[204:207], v[228:231], v[116:119]
	v_mfma_f32_16x16x32_bf16 v[120:123], v[220:223], v[228:231], v[120:123]
	v_mfma_f32_16x16x32_bf16 v[124:127], v[204:207], v[248:251], v[124:127]
	v_mfma_f32_16x16x32_bf16 v[128:131], v[220:223], v[248:251], v[128:131]
	s_setprio 0
	s_barrier
	s_andn2_b64 vcc, exec, s[48:49]
	s_cbranch_vccnz .LBB0_1177
	s_add_u32 s78, s26, 0x200
	s_addc_u32 s79, s27, 0
	s_add_u32 s50, s50, 0x200
	s_addc_u32 s51, s51, 0
	s_mov_b32 s80, 4
	.p2align	6
